# combine pass (old P4) fused into attention phase with a 2-group skew (half the CUs run it before, half after their attention units), one grid barrier removed; out-proj accumulators scaled by rstd_a mi
# speedup vs baseline: 1.0223x; 1.0062x over previous
.LBB0_392:
	s_cmp_lt_i32 s30, 4
	s_cselect_b64 s[2:3], -1, 0
	s_add_u32 s6, s28, 0x30000
	s_addc_u32 s7, s29, 0
	s_and_b64 s[8:9], s[2:3], s[0:1]
	s_andn2_b64 vcc, exec, s[8:9]
	s_cbranch_vccnz .LBB0_474
	s_bitcmp1_b32 s74, 6
	s_cbranch_scc1 .Lcomb_retA
	s_mov_b32 s101, 0
	s_branch .Lcomb
.Lcomb_retA:
	s_abs_i32 s2, s17
	s_waitcnt vmcnt(0)
	v_cvt_f32_u32_e32 v0, s2
	s_movk_i32 s0, 0x80
	v_cmp_gt_u32_e32 vcc, s0, v189
	s_sub_i32 s0, 0, s2
	v_rcp_iflag_f32_e32 v0, v0
	s_add_i32 s5, s17, 0x3ff
	s_abs_i32 s3, s5
	v_mul_f32_e32 v0, 0x4f7ffffe, v0
	v_cvt_u32_f32_e32 v0, v0
	s_nop 0
	v_readfirstlane_b32 s1, v0
	s_mul_i32 s0, s0, s1
	s_mul_hi_u32 s0, s1, s0
	s_add_i32 s1, s1, s0
	s_mul_hi_u32 s4, s3, s1
	s_and_saveexec_b64 s[0:1], vcc
	s_cbranch_execz .LBB0_395
	v_lshlrev_b32_e32 v0, 2, v189
	v_mov_b32_e32 v1, 0
	s_movk_i32 s10, 0xff00
	v_lshl_add_u64 v[4:5], s[44:45], 0, v[0:1]
	s_mov_b32 s11, -1
	v_lshl_add_u64 v[2:3], s[42:43], 0, v[0:1]
	v_lshl_add_u64 v[4:5], v[4:5], 0, s[10:11]
	v_cndmask_b32_e64 v3, v5, v3, s[76:77]
	v_cndmask_b32_e64 v2, v4, v2, s[76:77]
	global_load_dword v1, v[2:3], off
	s_add_i32 s10, 0, 0x20400
	v_add_u32_e32 v0, s10, v0
	s_waitcnt vmcnt(0)
	ds_write_b32 v0, v1 offset:8192

.LBB0_474:
	s_bitcmp1_b32 s74, 6
	s_cbranch_scc0 .Lcomb_retB
	s_mov_b32 s101, 1
	s_branch .Lcomb
.Lcomb_retB:
	s_mov_b64 s[2:3], -1
	s_branch .LBB0_534
.Lcomb:
	s_mov_b64 exec, -1
	v_lshlrev_b32_e32 v132, 5, v240
	v_lshlrev_b32_e32 v128, 4, v240
	global_load_dwordx4 v[120:123], v132, s[62:63]
	global_load_dwordx4 v[124:127], v132, s[62:63] offset:16
	s_lshl_b32 s98, s74, 10
	v_add_u32_e32 v133, s98, v128
	s_mul_i32 s98, s74, 0xe00
	s_addk_i32 s98, 0xa00
	v_add_u32_e32 v134, s98, v128
	s_lshl_b32 s98, s74, 11
	s_addk_i32 s98, 0x400
	v_add_u32_e32 v135, s98, v128
	v_mov_b32_e32 v140, 0x3d372713
	v_mov_b32_e32 v142, 0xc0135761
	v_mov_b32_e32 v131, 0x358637bd
	global_load_dwordx4 v[0:3], v133, s[22:23] nt
	global_load_dwordx4 v[4:7], v133, s[20:21] nt
	global_load_dwordx4 v[8:11], v134, s[38:39] nt
	v_add_u32_e32 v136, 0x200000, v133
	v_add_u32_e32 v137, 0x700000, v134
	global_load_dwordx4 v[12:15], v136, s[22:23] nt
	global_load_dwordx4 v[16:19], v136, s[20:21] nt
	global_load_dwordx4 v[20:23], v137, s[38:39] nt
	v_add_u32_e32 v136, 0x400000, v133
	v_add_u32_e32 v137, 0xe00000, v134
	global_load_dwordx4 v[24:27], v136, s[22:23] nt
	global_load_dwordx4 v[28:31], v136, s[20:21] nt
	global_load_dwordx4 v[32:35], v137, s[38:39] nt
	v_add_u32_e32 v136, 0x600000, v133
	v_add_u32_e32 v137, 0x1500000, v134
	global_load_dwordx4 v[36:39], v136, s[22:23] nt
	global_load_dwordx4 v[40:43], v136, s[20:21] nt
	global_load_dwordx4 v[44:47], v137, s[38:39] nt
	v_add_u32_e32 v136, 0x800000, v133
	v_add_u32_e32 v137, 0x1c00000, v134
	global_load_dwordx4 v[48:51], v136, s[22:23] nt
	global_load_dwordx4 v[52:55], v136, s[20:21] nt
	global_load_dwordx4 v[56:59], v137, s[38:39] nt
	v_add_u32_e32 v136, 0xa00000, v133
	v_add_u32_e32 v137, 0x2300000, v134
	global_load_dwordx4 v[60:63], v136, s[22:23] nt
	global_load_dwordx4 v[64:67], v136, s[20:21] nt
	global_load_dwordx4 v[68:71], v137, s[38:39] nt
	v_add_u32_e32 v136, 0xc00000, v133
	v_add_u32_e32 v137, 0x2a00000, v134
	global_load_dwordx4 v[72:75], v136, s[22:23] nt
	global_load_dwordx4 v[76:79], v136, s[20:21] nt
	global_load_dwordx4 v[80:83], v137, s[38:39] nt
	v_add_u32_e32 v136, 0xe00000, v133
	v_add_u32_e32 v137, 0x3100000, v134
	global_load_dwordx4 v[84:87], v136, s[22:23] nt
	global_load_dwordx4 v[88:91], v136, s[20:21] nt
	global_load_dwordx4 v[92:95], v137, s[38:39] nt
	s_waitcnt vmcnt(21)
	v_lshlrev_b32_e32 v104, 16, v0
	v_and_b32_e32 v105, 0xffff0000, v0
	v_lshlrev_b32_e32 v106, 16, v4
	v_and_b32_e32 v107, 0xffff0000, v4
	v_lshlrev_b32_e32 v108, 16, v8
	v_and_b32_e32 v109, 0xffff0000, v8
	v_pk_add_f32 v[104:105], v[104:105], v[106:107]
	v_pk_mul_f32 v[110:111], v[108:109], v[108:109]
	v_pk_fma_f32 v[110:111], v[110:111], v[140:141], 1.0 op_sel_hi:[1,0,0]
	v_pk_mul_f32 v[110:111], v[110:111], v[108:109]
	v_pk_mul_f32 v[110:111], v[110:111], v[142:143] op_sel_hi:[1,0]
	v_exp_f32_e32 v110, v110
	v_exp_f32_e32 v111, v111
	s_nop 0
	v_pk_add_f32 v[110:111], v[110:111], 1.0 op_sel_hi:[1,0]
	v_rcp_f32_e32 v110, v110
	v_rcp_f32_e32 v111, v111
	s_nop 0
	v_pk_mul_f32 v[110:111], v[110:111], v[108:109]
	v_pk_mul_f32 v[96:97], v[104:105], v[110:111]
	v_pk_mul_f32 v[112:113], v[96:97], v[96:97]
	v_lshlrev_b32_e32 v104, 16, v1
	v_and_b32_e32 v105, 0xffff0000, v1
	v_lshlrev_b32_e32 v106, 16, v5
	v_and_b32_e32 v107, 0xffff0000, v5
	v_lshlrev_b32_e32 v108, 16, v9
	v_and_b32_e32 v109, 0xffff0000, v9
	v_pk_add_f32 v[104:105], v[104:105], v[106:107]
	v_pk_mul_f32 v[110:111], v[108:109], v[108:109]
	v_pk_fma_f32 v[110:111], v[110:111], v[140:141], 1.0 op_sel_hi:[1,0,0]
	v_pk_mul_f32 v[110:111], v[110:111], v[108:109]
	v_pk_mul_f32 v[110:111], v[110:111], v[142:143] op_sel_hi:[1,0]
	v_exp_f32_e32 v110, v110
	v_exp_f32_e32 v111, v111
	s_nop 0
	v_pk_add_f32 v[110:111], v[110:111], 1.0 op_sel_hi:[1,0]
	v_rcp_f32_e32 v110, v110
	v_rcp_f32_e32 v111, v111
	s_nop 0
	v_pk_mul_f32 v[110:111], v[110:111], v[108:109]
	v_pk_mul_f32 v[98:99], v[104:105], v[110:111]
	v_pk_fma_f32 v[112:113], v[98:99], v[98:99], v[112:113]
	v_lshlrev_b32_e32 v104, 16, v2
	v_and_b32_e32 v105, 0xffff0000, v2
	v_lshlrev_b32_e32 v106, 16, v6
	v_and_b32_e32 v107, 0xffff0000, v6
	v_lshlrev_b32_e32 v108, 16, v10
	v_and_b32_e32 v109, 0xffff0000, v10
	v_pk_add_f32 v[104:105], v[104:105], v[106:107]
	v_pk_mul_f32 v[110:111], v[108:109], v[108:109]
	v_pk_fma_f32 v[110:111], v[110:111], v[140:141], 1.0 op_sel_hi:[1,0,0]
	v_pk_mul_f32 v[110:111], v[110:111], v[108:109]
	v_pk_mul_f32 v[110:111], v[110:111], v[142:143] op_sel_hi:[1,0]
	v_exp_f32_e32 v110, v110
	v_exp_f32_e32 v111, v111
	s_nop 0
	v_pk_add_f32 v[110:111], v[110:111], 1.0 op_sel_hi:[1,0]
	v_rcp_f32_e32 v110, v110
	v_rcp_f32_e32 v111, v111
	s_nop 0
	v_pk_mul_f32 v[110:111], v[110:111], v[108:109]
	v_pk_mul_f32 v[100:101], v[104:105], v[110:111]
	v_pk_fma_f32 v[112:113], v[100:101], v[100:101], v[112:113]
	v_lshlrev_b32_e32 v104, 16, v3
	v_and_b32_e32 v105, 0xffff0000, v3
	v_lshlrev_b32_e32 v106, 16, v7
	v_and_b32_e32 v107, 0xffff0000, v7
	v_lshlrev_b32_e32 v108, 16, v11
	v_and_b32_e32 v109, 0xffff0000, v11
	v_pk_add_f32 v[104:105], v[104:105], v[106:107]
	v_pk_mul_f32 v[110:111], v[108:109], v[108:109]
	v_pk_fma_f32 v[110:111], v[110:111], v[140:141], 1.0 op_sel_hi:[1,0,0]
	v_pk_mul_f32 v[110:111], v[110:111], v[108:109]
	v_pk_mul_f32 v[110:111], v[110:111], v[142:143] op_sel_hi:[1,0]
	v_exp_f32_e32 v110, v110
	v_exp_f32_e32 v111, v111
	s_nop 0
	v_pk_add_f32 v[110:111], v[110:111], 1.0 op_sel_hi:[1,0]
	v_rcp_f32_e32 v110, v110
	v_rcp_f32_e32 v111, v111
	s_nop 0
	v_pk_mul_f32 v[110:111], v[110:111], v[108:109]
	v_pk_mul_f32 v[102:103], v[104:105], v[110:111]
	v_pk_fma_f32 v[112:113], v[102:103], v[102:103], v[112:113]
	v_add_f32_e32 v112, v112, v113
	s_nop 1
	v_add_f32_dpp v112, v112, v112 quad_perm:[1,0,3,2] row_mask:0xf bank_mask:0xf
	s_nop 1
	v_add_f32_dpp v112, v112, v112 quad_perm:[2,3,0,1] row_mask:0xf bank_mask:0xf
	s_nop 1
	v_add_f32_dpp v112, v112, v112 row_half_mirror row_mask:0xf bank_mask:0xf
	s_nop 1
	v_add_f32_dpp v112, v112, v112 row_mirror row_mask:0xf bank_mask:0xf
	s_nop 1
	v_readlane_b32 s98, v112, 0
	v_readlane_b32 s99, v112, 16
	v_readlane_b32 s100, v112, 32
	v_readlane_b32 vcc_lo, v112, 48
	s_nop 1
	v_mov_b32_e32 v113, s98
	v_add_f32_e32 v113, s99, v113
	v_add_f32_e32 v113, s100, v113
	v_add_f32_e32 v113, vcc_lo, v113
	v_fmamk_f32 v144, v113, 0x3b000000, v131
	v_rsq_f32_e32 v144, v144
	s_nop 0
	v_pk_mul_f32 v[104:105], v[96:97], v[144:145] op_sel_hi:[1,0]
	v_pk_mul_f32 v[104:105], v[104:105], v[120:121]
	v_cvt_pk_bf16_f32 v116, v104, v105
	v_pk_mul_f32 v[104:105], v[98:99], v[144:145] op_sel_hi:[1,0]
	v_pk_mul_f32 v[104:105], v[104:105], v[122:123]
	v_cvt_pk_bf16_f32 v117, v104, v105
	v_pk_mul_f32 v[104:105], v[100:101], v[144:145] op_sel_hi:[1,0]
	v_pk_mul_f32 v[104:105], v[104:105], v[124:125]
	v_cvt_pk_bf16_f32 v118, v104, v105
	v_pk_mul_f32 v[104:105], v[102:103], v[144:145] op_sel_hi:[1,0]
	v_pk_mul_f32 v[104:105], v[104:105], v[126:127]
	v_cvt_pk_bf16_f32 v119, v104, v105
	global_store_dwordx4 v135, v[116:119], s[34:35]
	v_add_u32_e32 v136, 0x1000000, v133
	v_add_u32_e32 v137, 0x3800000, v134
	global_load_dwordx4 v[0:3], v136, s[22:23] nt
	global_load_dwordx4 v[4:7], v136, s[20:21] nt
	global_load_dwordx4 v[8:11], v137, s[38:39] nt
	s_waitcnt vmcnt(22)
	v_lshlrev_b32_e32 v104, 16, v12
	v_and_b32_e32 v105, 0xffff0000, v12
	v_lshlrev_b32_e32 v106, 16, v16
	v_and_b32_e32 v107, 0xffff0000, v16
	v_lshlrev_b32_e32 v108, 16, v20
	v_and_b32_e32 v109, 0xffff0000, v20
	v_pk_add_f32 v[104:105], v[104:105], v[106:107]
	v_pk_mul_f32 v[110:111], v[108:109], v[108:109]
	v_pk_fma_f32 v[110:111], v[110:111], v[140:141], 1.0 op_sel_hi:[1,0,0]
	v_pk_mul_f32 v[110:111], v[110:111], v[108:109]
	v_pk_mul_f32 v[110:111], v[110:111], v[142:143] op_sel_hi:[1,0]
	v_exp_f32_e32 v110, v110
	v_exp_f32_e32 v111, v111
	s_nop 0
	v_pk_add_f32 v[110:111], v[110:111], 1.0 op_sel_hi:[1,0]
	v_rcp_f32_e32 v110, v110
	v_rcp_f32_e32 v111, v111
	s_nop 0
	v_pk_mul_f32 v[110:111], v[110:111], v[108:109]
	v_pk_mul_f32 v[96:97], v[104:105], v[110:111]
	v_pk_mul_f32 v[112:113], v[96:97], v[96:97]
	v_lshlrev_b32_e32 v104, 16, v13
	v_and_b32_e32 v105, 0xffff0000, v13
	v_lshlrev_b32_e32 v106, 16, v17
	v_and_b32_e32 v107, 0xffff0000, v17
	v_lshlrev_b32_e32 v108, 16, v21
	v_and_b32_e32 v109, 0xffff0000, v21
	v_pk_add_f32 v[104:105], v[104:105], v[106:107]
	v_pk_mul_f32 v[110:111], v[108:109], v[108:109]
	v_pk_fma_f32 v[110:111], v[110:111], v[140:141], 1.0 op_sel_hi:[1,0,0]
	v_pk_mul_f32 v[110:111], v[110:111], v[108:109]
	v_pk_mul_f32 v[110:111], v[110:111], v[142:143] op_sel_hi:[1,0]
	v_exp_f32_e32 v110, v110
	v_exp_f32_e32 v111, v111
	s_nop 0
	v_pk_add_f32 v[110:111], v[110:111], 1.0 op_sel_hi:[1,0]
	v_rcp_f32_e32 v110, v110
	v_rcp_f32_e32 v111, v111
	s_nop 0
	v_pk_mul_f32 v[110:111], v[110:111], v[108:109]
	v_pk_mul_f32 v[98:99], v[104:105], v[110:111]
	v_pk_fma_f32 v[112:113], v[98:99], v[98:99], v[112:113]
	v_lshlrev_b32_e32 v104, 16, v14
	v_and_b32_e32 v105, 0xffff0000, v14
	v_lshlrev_b32_e32 v106, 16, v18
	v_and_b32_e32 v107, 0xffff0000, v18
	v_lshlrev_b32_e32 v108, 16, v22
	v_and_b32_e32 v109, 0xffff0000, v22
	v_pk_add_f32 v[104:105], v[104:105], v[106:107]
	v_pk_mul_f32 v[110:111], v[108:109], v[108:109]
	v_pk_fma_f32 v[110:111], v[110:111], v[140:141], 1.0 op_sel_hi:[1,0,0]
	v_pk_mul_f32 v[110:111], v[110:111], v[108:109]
	v_pk_mul_f32 v[110:111], v[110:111], v[142:143] op_sel_hi:[1,0]
	v_exp_f32_e32 v110, v110
	v_exp_f32_e32 v111, v111
	s_nop 0
	v_pk_add_f32 v[110:111], v[110:111], 1.0 op_sel_hi:[1,0]
	v_rcp_f32_e32 v110, v110
	v_rcp_f32_e32 v111, v111
	s_nop 0
	v_pk_mul_f32 v[110:111], v[110:111], v[108:109]
	v_pk_mul_f32 v[100:101], v[104:105], v[110:111]
	v_pk_fma_f32 v[112:113], v[100:101], v[100:101], v[112:113]
	v_lshlrev_b32_e32 v104, 16, v15
	v_and_b32_e32 v105, 0xffff0000, v15
	v_lshlrev_b32_e32 v106, 16, v19
	v_and_b32_e32 v107, 0xffff0000, v19
	v_lshlrev_b32_e32 v108, 16, v23
	v_and_b32_e32 v109, 0xffff0000, v23
	v_pk_add_f32 v[104:105], v[104:105], v[106:107]
	v_pk_mul_f32 v[110:111], v[108:109], v[108:109]
	v_pk_fma_f32 v[110:111], v[110:111], v[140:141], 1.0 op_sel_hi:[1,0,0]
	v_pk_mul_f32 v[110:111], v[110:111], v[108:109]
	v_pk_mul_f32 v[110:111], v[110:111], v[142:143] op_sel_hi:[1,0]
	v_exp_f32_e32 v110, v110
	v_exp_f32_e32 v111, v111
	s_nop 0
	v_pk_add_f32 v[110:111], v[110:111], 1.0 op_sel_hi:[1,0]
	v_rcp_f32_e32 v110, v110
	v_rcp_f32_e32 v111, v111
	s_nop 0
	v_pk_mul_f32 v[110:111], v[110:111], v[108:109]
	v_pk_mul_f32 v[102:103], v[104:105], v[110:111]
	v_pk_fma_f32 v[112:113], v[102:103], v[102:103], v[112:113]
	v_add_f32_e32 v112, v112, v113
	s_nop 1
	v_add_f32_dpp v112, v112, v112 quad_perm:[1,0,3,2] row_mask:0xf bank_mask:0xf
	s_nop 1
	v_add_f32_dpp v112, v112, v112 quad_perm:[2,3,0,1] row_mask:0xf bank_mask:0xf
	s_nop 1
	v_add_f32_dpp v112, v112, v112 row_half_mirror row_mask:0xf bank_mask:0xf
	s_nop 1
	v_add_f32_dpp v112, v112, v112 row_mirror row_mask:0xf bank_mask:0xf
	s_nop 1
	v_readlane_b32 s98, v112, 0
	v_readlane_b32 s99, v112, 16
	v_readlane_b32 s100, v112, 32
	v_readlane_b32 vcc_lo, v112, 48
	s_nop 1
	v_mov_b32_e32 v113, s98
	v_add_f32_e32 v113, s99, v113
	v_add_f32_e32 v113, s100, v113
	v_add_f32_e32 v113, vcc_lo, v113
	v_fmamk_f32 v144, v113, 0x3b000000, v131
	v_rsq_f32_e32 v144, v144
	s_nop 0
	v_pk_mul_f32 v[104:105], v[96:97], v[144:145] op_sel_hi:[1,0]
	v_pk_mul_f32 v[104:105], v[104:105], v[120:121]
	v_cvt_pk_bf16_f32 v116, v104, v105
	v_pk_mul_f32 v[104:105], v[98:99], v[144:145] op_sel_hi:[1,0]
	v_pk_mul_f32 v[104:105], v[104:105], v[122:123]
	v_cvt_pk_bf16_f32 v117, v104, v105
	v_pk_mul_f32 v[104:105], v[100:101], v[144:145] op_sel_hi:[1,0]
	v_pk_mul_f32 v[104:105], v[104:105], v[124:125]
	v_cvt_pk_bf16_f32 v118, v104, v105
	v_pk_mul_f32 v[104:105], v[102:103], v[144:145] op_sel_hi:[1,0]
	v_pk_mul_f32 v[104:105], v[104:105], v[126:127]
	v_cvt_pk_bf16_f32 v119, v104, v105
	v_add_u32_e32 v138, 0x400000, v135
	global_store_dwordx4 v138, v[116:119], s[34:35]
	v_add_u32_e32 v136, 0x1200000, v133
	v_add_u32_e32 v137, 0x3f00000, v134
	global_load_dwordx4 v[12:15], v136, s[22:23] nt
	global_load_dwordx4 v[16:19], v136, s[20:21] nt
	global_load_dwordx4 v[20:23], v137, s[38:39] nt
	s_waitcnt vmcnt(23)
	v_lshlrev_b32_e32 v104, 16, v24
	v_and_b32_e32 v105, 0xffff0000, v24
	v_lshlrev_b32_e32 v106, 16, v28
	v_and_b32_e32 v107, 0xffff0000, v28
	v_lshlrev_b32_e32 v108, 16, v32
	v_and_b32_e32 v109, 0xffff0000, v32
	v_pk_add_f32 v[104:105], v[104:105], v[106:107]
	v_pk_mul_f32 v[110:111], v[108:109], v[108:109]
	v_pk_fma_f32 v[110:111], v[110:111], v[140:141], 1.0 op_sel_hi:[1,0,0]
	v_pk_mul_f32 v[110:111], v[110:111], v[108:109]
	v_pk_mul_f32 v[110:111], v[110:111], v[142:143] op_sel_hi:[1,0]
	v_exp_f32_e32 v110, v110
	v_exp_f32_e32 v111, v111
	s_nop 0
	v_pk_add_f32 v[110:111], v[110:111], 1.0 op_sel_hi:[1,0]
	v_rcp_f32_e32 v110, v110
	v_rcp_f32_e32 v111, v111
	s_nop 0
	v_pk_mul_f32 v[110:111], v[110:111], v[108:109]
	v_pk_mul_f32 v[96:97], v[104:105], v[110:111]
	v_pk_mul_f32 v[112:113], v[96:97], v[96:97]
	v_lshlrev_b32_e32 v104, 16, v25
	v_and_b32_e32 v105, 0xffff0000, v25
	v_lshlrev_b32_e32 v106, 16, v29
	v_and_b32_e32 v107, 0xffff0000, v29
	v_lshlrev_b32_e32 v108, 16, v33
	v_and_b32_e32 v109, 0xffff0000, v33
	v_pk_add_f32 v[104:105], v[104:105], v[106:107]
	v_pk_mul_f32 v[110:111], v[108:109], v[108:109]
	v_pk_fma_f32 v[110:111], v[110:111], v[140:141], 1.0 op_sel_hi:[1,0,0]
	v_pk_mul_f32 v[110:111], v[110:111], v[108:109]
	v_pk_mul_f32 v[110:111], v[110:111], v[142:143] op_sel_hi:[1,0]
	v_exp_f32_e32 v110, v110
	v_exp_f32_e32 v111, v111
	s_nop 0
	v_pk_add_f32 v[110:111], v[110:111], 1.0 op_sel_hi:[1,0]
	v_rcp_f32_e32 v110, v110
	v_rcp_f32_e32 v111, v111
	s_nop 0
	v_pk_mul_f32 v[110:111], v[110:111], v[108:109]
	v_pk_mul_f32 v[98:99], v[104:105], v[110:111]
	v_pk_fma_f32 v[112:113], v[98:99], v[98:99], v[112:113]
	v_lshlrev_b32_e32 v104, 16, v26
	v_and_b32_e32 v105, 0xffff0000, v26
	v_lshlrev_b32_e32 v106, 16, v30
	v_and_b32_e32 v107, 0xffff0000, v30
	v_lshlrev_b32_e32 v108, 16, v34
	v_and_b32_e32 v109, 0xffff0000, v34
	v_pk_add_f32 v[104:105], v[104:105], v[106:107]
	v_pk_mul_f32 v[110:111], v[108:109], v[108:109]
	v_pk_fma_f32 v[110:111], v[110:111], v[140:141], 1.0 op_sel_hi:[1,0,0]
	v_pk_mul_f32 v[110:111], v[110:111], v[108:109]
	v_pk_mul_f32 v[110:111], v[110:111], v[142:143] op_sel_hi:[1,0]
	v_exp_f32_e32 v110, v110
	v_exp_f32_e32 v111, v111
	s_nop 0
	v_pk_add_f32 v[110:111], v[110:111], 1.0 op_sel_hi:[1,0]
	v_rcp_f32_e32 v110, v110
	v_rcp_f32_e32 v111, v111
	s_nop 0
	v_pk_mul_f32 v[110:111], v[110:111], v[108:109]
	v_pk_mul_f32 v[100:101], v[104:105], v[110:111]
	v_pk_fma_f32 v[112:113], v[100:101], v[100:101], v[112:113]
	v_lshlrev_b32_e32 v104, 16, v27
	v_and_b32_e32 v105, 0xffff0000, v27
	v_lshlrev_b32_e32 v106, 16, v31
	v_and_b32_e32 v107, 0xffff0000, v31
	v_lshlrev_b32_e32 v108, 16, v35
	v_and_b32_e32 v109, 0xffff0000, v35
	v_pk_add_f32 v[104:105], v[104:105], v[106:107]
	v_pk_mul_f32 v[110:111], v[108:109], v[108:109]
	v_pk_fma_f32 v[110:111], v[110:111], v[140:141], 1.0 op_sel_hi:[1,0,0]
	v_pk_mul_f32 v[110:111], v[110:111], v[108:109]
	v_pk_mul_f32 v[110:111], v[110:111], v[142:143] op_sel_hi:[1,0]
	v_exp_f32_e32 v110, v110
	v_exp_f32_e32 v111, v111
	s_nop 0
	v_pk_add_f32 v[110:111], v[110:111], 1.0 op_sel_hi:[1,0]
	v_rcp_f32_e32 v110, v110
	v_rcp_f32_e32 v111, v111
	s_nop 0
	v_pk_mul_f32 v[110:111], v[110:111], v[108:109]
	v_pk_mul_f32 v[102:103], v[104:105], v[110:111]
	v_pk_fma_f32 v[112:113], v[102:103], v[102:103], v[112:113]
	v_add_f32_e32 v112, v112, v113
	s_nop 1
	v_add_f32_dpp v112, v112, v112 quad_perm:[1,0,3,2] row_mask:0xf bank_mask:0xf
	s_nop 1
	v_add_f32_dpp v112, v112, v112 quad_perm:[2,3,0,1] row_mask:0xf bank_mask:0xf
	s_nop 1
	v_add_f32_dpp v112, v112, v112 row_half_mirror row_mask:0xf bank_mask:0xf
	s_nop 1
	v_add_f32_dpp v112, v112, v112 row_mirror row_mask:0xf bank_mask:0xf
	s_nop 1
	v_readlane_b32 s98, v112, 0
	v_readlane_b32 s99, v112, 16
	v_readlane_b32 s100, v112, 32
	v_readlane_b32 vcc_lo, v112, 48
	s_nop 1
	v_mov_b32_e32 v113, s98
	v_add_f32_e32 v113, s99, v113
	v_add_f32_e32 v113, s100, v113
	v_add_f32_e32 v113, vcc_lo, v113
	v_fmamk_f32 v144, v113, 0x3b000000, v131
	v_rsq_f32_e32 v144, v144
	s_nop 0
	v_pk_mul_f32 v[104:105], v[96:97], v[144:145] op_sel_hi:[1,0]
	v_pk_mul_f32 v[104:105], v[104:105], v[120:121]
	v_cvt_pk_bf16_f32 v116, v104, v105
	v_pk_mul_f32 v[104:105], v[98:99], v[144:145] op_sel_hi:[1,0]
	v_pk_mul_f32 v[104:105], v[104:105], v[122:123]
	v_cvt_pk_bf16_f32 v117, v104, v105
	v_pk_mul_f32 v[104:105], v[100:101], v[144:145] op_sel_hi:[1,0]
	v_pk_mul_f32 v[104:105], v[104:105], v[124:125]
	v_cvt_pk_bf16_f32 v118, v104, v105
	v_pk_mul_f32 v[104:105], v[102:103], v[144:145] op_sel_hi:[1,0]
	v_pk_mul_f32 v[104:105], v[104:105], v[126:127]
	v_cvt_pk_bf16_f32 v119, v104, v105
	v_add_u32_e32 v138, 0x800000, v135
	global_store_dwordx4 v138, v[116:119], s[34:35]
	v_add_u32_e32 v136, 0x1400000, v133
	v_add_u32_e32 v137, 0x4600000, v134
	global_load_dwordx4 v[24:27], v136, s[22:23] nt
	global_load_dwordx4 v[28:31], v136, s[20:21] nt
	global_load_dwordx4 v[32:35], v137, s[38:39] nt
	s_waitcnt vmcnt(24)
	v_lshlrev_b32_e32 v104, 16, v36
	v_and_b32_e32 v105, 0xffff0000, v36
	v_lshlrev_b32_e32 v106, 16, v40
	v_and_b32_e32 v107, 0xffff0000, v40
	v_lshlrev_b32_e32 v108, 16, v44
	v_and_b32_e32 v109, 0xffff0000, v44
	v_pk_add_f32 v[104:105], v[104:105], v[106:107]
	v_pk_mul_f32 v[110:111], v[108:109], v[108:109]
	v_pk_fma_f32 v[110:111], v[110:111], v[140:141], 1.0 op_sel_hi:[1,0,0]
	v_pk_mul_f32 v[110:111], v[110:111], v[108:109]
	v_pk_mul_f32 v[110:111], v[110:111], v[142:143] op_sel_hi:[1,0]
	v_exp_f32_e32 v110, v110
	v_exp_f32_e32 v111, v111
	s_nop 0
	v_pk_add_f32 v[110:111], v[110:111], 1.0 op_sel_hi:[1,0]
	v_rcp_f32_e32 v110, v110
	v_rcp_f32_e32 v111, v111
	s_nop 0
	v_pk_mul_f32 v[110:111], v[110:111], v[108:109]
	v_pk_mul_f32 v[96:97], v[104:105], v[110:111]
	v_pk_mul_f32 v[112:113], v[96:97], v[96:97]
	v_lshlrev_b32_e32 v104, 16, v37
	v_and_b32_e32 v105, 0xffff0000, v37
	v_lshlrev_b32_e32 v106, 16, v41
	v_and_b32_e32 v107, 0xffff0000, v41
	v_lshlrev_b32_e32 v108, 16, v45
	v_and_b32_e32 v109, 0xffff0000, v45
	v_pk_add_f32 v[104:105], v[104:105], v[106:107]
	v_pk_mul_f32 v[110:111], v[108:109], v[108:109]
	v_pk_fma_f32 v[110:111], v[110:111], v[140:141], 1.0 op_sel_hi:[1,0,0]
	v_pk_mul_f32 v[110:111], v[110:111], v[108:109]
	v_pk_mul_f32 v[110:111], v[110:111], v[142:143] op_sel_hi:[1,0]
	v_exp_f32_e32 v110, v110
	v_exp_f32_e32 v111, v111
	s_nop 0
	v_pk_add_f32 v[110:111], v[110:111], 1.0 op_sel_hi:[1,0]
	v_rcp_f32_e32 v110, v110
	v_rcp_f32_e32 v111, v111
	s_nop 0
	v_pk_mul_f32 v[110:111], v[110:111], v[108:109]
	v_pk_mul_f32 v[98:99], v[104:105], v[110:111]
	v_pk_fma_f32 v[112:113], v[98:99], v[98:99], v[112:113]
	v_lshlrev_b32_e32 v104, 16, v38
	v_and_b32_e32 v105, 0xffff0000, v38
	v_lshlrev_b32_e32 v106, 16, v42
	v_and_b32_e32 v107, 0xffff0000, v42
	v_lshlrev_b32_e32 v108, 16, v46
	v_and_b32_e32 v109, 0xffff0000, v46
	v_pk_add_f32 v[104:105], v[104:105], v[106:107]
	v_pk_mul_f32 v[110:111], v[108:109], v[108:109]
	v_pk_fma_f32 v[110:111], v[110:111], v[140:141], 1.0 op_sel_hi:[1,0,0]
	v_pk_mul_f32 v[110:111], v[110:111], v[108:109]
	v_pk_mul_f32 v[110:111], v[110:111], v[142:143] op_sel_hi:[1,0]
	v_exp_f32_e32 v110, v110
	v_exp_f32_e32 v111, v111
	s_nop 0
	v_pk_add_f32 v[110:111], v[110:111], 1.0 op_sel_hi:[1,0]
	v_rcp_f32_e32 v110, v110
	v_rcp_f32_e32 v111, v111
	s_nop 0
	v_pk_mul_f32 v[110:111], v[110:111], v[108:109]
	v_pk_mul_f32 v[100:101], v[104:105], v[110:111]
	v_pk_fma_f32 v[112:113], v[100:101], v[100:101], v[112:113]
	v_lshlrev_b32_e32 v104, 16, v39
	v_and_b32_e32 v105, 0xffff0000, v39
	v_lshlrev_b32_e32 v106, 16, v43
	v_and_b32_e32 v107, 0xffff0000, v43
	v_lshlrev_b32_e32 v108, 16, v47
	v_and_b32_e32 v109, 0xffff0000, v47
	v_pk_add_f32 v[104:105], v[104:105], v[106:107]
	v_pk_mul_f32 v[110:111], v[108:109], v[108:109]
	v_pk_fma_f32 v[110:111], v[110:111], v[140:141], 1.0 op_sel_hi:[1,0,0]
	v_pk_mul_f32 v[110:111], v[110:111], v[108:109]
	v_pk_mul_f32 v[110:111], v[110:111], v[142:143] op_sel_hi:[1,0]
	v_exp_f32_e32 v110, v110
	v_exp_f32_e32 v111, v111
	s_nop 0
	v_pk_add_f32 v[110:111], v[110:111], 1.0 op_sel_hi:[1,0]
	v_rcp_f32_e32 v110, v110
	v_rcp_f32_e32 v111, v111
	s_nop 0
	v_pk_mul_f32 v[110:111], v[110:111], v[108:109]
	v_pk_mul_f32 v[102:103], v[104:105], v[110:111]
	v_pk_fma_f32 v[112:113], v[102:103], v[102:103], v[112:113]
	v_add_f32_e32 v112, v112, v113
	s_nop 1
	v_add_f32_dpp v112, v112, v112 quad_perm:[1,0,3,2] row_mask:0xf bank_mask:0xf
	s_nop 1
	v_add_f32_dpp v112, v112, v112 quad_perm:[2,3,0,1] row_mask:0xf bank_mask:0xf
	s_nop 1
	v_add_f32_dpp v112, v112, v112 row_half_mirror row_mask:0xf bank_mask:0xf
	s_nop 1
	v_add_f32_dpp v112, v112, v112 row_mirror row_mask:0xf bank_mask:0xf
	s_nop 1
	v_readlane_b32 s98, v112, 0
	v_readlane_b32 s99, v112, 16
	v_readlane_b32 s100, v112, 32
	v_readlane_b32 vcc_lo, v112, 48
	s_nop 1
	v_mov_b32_e32 v113, s98
	v_add_f32_e32 v113, s99, v113
	v_add_f32_e32 v113, s100, v113
	v_add_f32_e32 v113, vcc_lo, v113
	v_fmamk_f32 v144, v113, 0x3b000000, v131
	v_rsq_f32_e32 v144, v144
	s_nop 0
	v_pk_mul_f32 v[104:105], v[96:97], v[144:145] op_sel_hi:[1,0]
	v_pk_mul_f32 v[104:105], v[104:105], v[120:121]
	v_cvt_pk_bf16_f32 v116, v104, v105
	v_pk_mul_f32 v[104:105], v[98:99], v[144:145] op_sel_hi:[1,0]
	v_pk_mul_f32 v[104:105], v[104:105], v[122:123]
	v_cvt_pk_bf16_f32 v117, v104, v105
	v_pk_mul_f32 v[104:105], v[100:101], v[144:145] op_sel_hi:[1,0]
	v_pk_mul_f32 v[104:105], v[104:105], v[124:125]
	v_cvt_pk_bf16_f32 v118, v104, v105
	v_pk_mul_f32 v[104:105], v[102:103], v[144:145] op_sel_hi:[1,0]
	v_pk_mul_f32 v[104:105], v[104:105], v[126:127]
	v_cvt_pk_bf16_f32 v119, v104, v105
	v_add_u32_e32 v138, 0xc00000, v135
	global_store_dwordx4 v138, v[116:119], s[34:35]
	v_add_u32_e32 v136, 0x1600000, v133
	v_add_u32_e32 v137, 0x4d00000, v134
	global_load_dwordx4 v[36:39], v136, s[22:23] nt
	global_load_dwordx4 v[40:43], v136, s[20:21] nt
	global_load_dwordx4 v[44:47], v137, s[38:39] nt
	s_waitcnt vmcnt(25)
	v_lshlrev_b32_e32 v104, 16, v48
	v_and_b32_e32 v105, 0xffff0000, v48
	v_lshlrev_b32_e32 v106, 16, v52
	v_and_b32_e32 v107, 0xffff0000, v52
	v_lshlrev_b32_e32 v108, 16, v56
	v_and_b32_e32 v109, 0xffff0000, v56
	v_pk_add_f32 v[104:105], v[104:105], v[106:107]
	v_pk_mul_f32 v[110:111], v[108:109], v[108:109]
	v_pk_fma_f32 v[110:111], v[110:111], v[140:141], 1.0 op_sel_hi:[1,0,0]
	v_pk_mul_f32 v[110:111], v[110:111], v[108:109]
	v_pk_mul_f32 v[110:111], v[110:111], v[142:143] op_sel_hi:[1,0]
	v_exp_f32_e32 v110, v110
	v_exp_f32_e32 v111, v111
	s_nop 0
	v_pk_add_f32 v[110:111], v[110:111], 1.0 op_sel_hi:[1,0]
	v_rcp_f32_e32 v110, v110
	v_rcp_f32_e32 v111, v111
	s_nop 0
	v_pk_mul_f32 v[110:111], v[110:111], v[108:109]
	v_pk_mul_f32 v[96:97], v[104:105], v[110:111]
	v_pk_mul_f32 v[112:113], v[96:97], v[96:97]
	v_lshlrev_b32_e32 v104, 16, v49
	v_and_b32_e32 v105, 0xffff0000, v49
	v_lshlrev_b32_e32 v106, 16, v53
	v_and_b32_e32 v107, 0xffff0000, v53
	v_lshlrev_b32_e32 v108, 16, v57
	v_and_b32_e32 v109, 0xffff0000, v57
	v_pk_add_f32 v[104:105], v[104:105], v[106:107]
	v_pk_mul_f32 v[110:111], v[108:109], v[108:109]
	v_pk_fma_f32 v[110:111], v[110:111], v[140:141], 1.0 op_sel_hi:[1,0,0]
	v_pk_mul_f32 v[110:111], v[110:111], v[108:109]
	v_pk_mul_f32 v[110:111], v[110:111], v[142:143] op_sel_hi:[1,0]
	v_exp_f32_e32 v110, v110
	v_exp_f32_e32 v111, v111
	s_nop 0
	v_pk_add_f32 v[110:111], v[110:111], 1.0 op_sel_hi:[1,0]
	v_rcp_f32_e32 v110, v110
	v_rcp_f32_e32 v111, v111
	s_nop 0
	v_pk_mul_f32 v[110:111], v[110:111], v[108:109]
	v_pk_mul_f32 v[98:99], v[104:105], v[110:111]
	v_pk_fma_f32 v[112:113], v[98:99], v[98:99], v[112:113]
	v_lshlrev_b32_e32 v104, 16, v50
	v_and_b32_e32 v105, 0xffff0000, v50
	v_lshlrev_b32_e32 v106, 16, v54
	v_and_b32_e32 v107, 0xffff0000, v54
	v_lshlrev_b32_e32 v108, 16, v58
	v_and_b32_e32 v109, 0xffff0000, v58
	v_pk_add_f32 v[104:105], v[104:105], v[106:107]
	v_pk_mul_f32 v[110:111], v[108:109], v[108:109]
	v_pk_fma_f32 v[110:111], v[110:111], v[140:141], 1.0 op_sel_hi:[1,0,0]
	v_pk_mul_f32 v[110:111], v[110:111], v[108:109]
	v_pk_mul_f32 v[110:111], v[110:111], v[142:143] op_sel_hi:[1,0]
	v_exp_f32_e32 v110, v110
	v_exp_f32_e32 v111, v111
	s_nop 0
	v_pk_add_f32 v[110:111], v[110:111], 1.0 op_sel_hi:[1,0]
	v_rcp_f32_e32 v110, v110
	v_rcp_f32_e32 v111, v111
	s_nop 0
	v_pk_mul_f32 v[110:111], v[110:111], v[108:109]
	v_pk_mul_f32 v[100:101], v[104:105], v[110:111]
	v_pk_fma_f32 v[112:113], v[100:101], v[100:101], v[112:113]
	v_lshlrev_b32_e32 v104, 16, v51
	v_and_b32_e32 v105, 0xffff0000, v51
	v_lshlrev_b32_e32 v106, 16, v55
	v_and_b32_e32 v107, 0xffff0000, v55
	v_lshlrev_b32_e32 v108, 16, v59
	v_and_b32_e32 v109, 0xffff0000, v59
	v_pk_add_f32 v[104:105], v[104:105], v[106:107]
	v_pk_mul_f32 v[110:111], v[108:109], v[108:109]
	v_pk_fma_f32 v[110:111], v[110:111], v[140:141], 1.0 op_sel_hi:[1,0,0]
	v_pk_mul_f32 v[110:111], v[110:111], v[108:109]
	v_pk_mul_f32 v[110:111], v[110:111], v[142:143] op_sel_hi:[1,0]
	v_exp_f32_e32 v110, v110
	v_exp_f32_e32 v111, v111
	s_nop 0
	v_pk_add_f32 v[110:111], v[110:111], 1.0 op_sel_hi:[1,0]
	v_rcp_f32_e32 v110, v110
	v_rcp_f32_e32 v111, v111
	s_nop 0
	v_pk_mul_f32 v[110:111], v[110:111], v[108:109]
	v_pk_mul_f32 v[102:103], v[104:105], v[110:111]
	v_pk_fma_f32 v[112:113], v[102:103], v[102:103], v[112:113]
	v_add_f32_e32 v112, v112, v113
	s_nop 1
	v_add_f32_dpp v112, v112, v112 quad_perm:[1,0,3,2] row_mask:0xf bank_mask:0xf
	s_nop 1
	v_add_f32_dpp v112, v112, v112 quad_perm:[2,3,0,1] row_mask:0xf bank_mask:0xf
	s_nop 1
	v_add_f32_dpp v112, v112, v112 row_half_mirror row_mask:0xf bank_mask:0xf
	s_nop 1
	v_add_f32_dpp v112, v112, v112 row_mirror row_mask:0xf bank_mask:0xf
	s_nop 1
	v_readlane_b32 s98, v112, 0
	v_readlane_b32 s99, v112, 16
	v_readlane_b32 s100, v112, 32
	v_readlane_b32 vcc_lo, v112, 48
	s_nop 1
	v_mov_b32_e32 v113, s98
	v_add_f32_e32 v113, s99, v113
	v_add_f32_e32 v113, s100, v113
	v_add_f32_e32 v113, vcc_lo, v113
	v_fmamk_f32 v144, v113, 0x3b000000, v131
	v_rsq_f32_e32 v144, v144
	s_nop 0
	v_pk_mul_f32 v[104:105], v[96:97], v[144:145] op_sel_hi:[1,0]
	v_pk_mul_f32 v[104:105], v[104:105], v[120:121]
	v_cvt_pk_bf16_f32 v116, v104, v105
	v_pk_mul_f32 v[104:105], v[98:99], v[144:145] op_sel_hi:[1,0]
	v_pk_mul_f32 v[104:105], v[104:105], v[122:123]
	v_cvt_pk_bf16_f32 v117, v104, v105
	v_pk_mul_f32 v[104:105], v[100:101], v[144:145] op_sel_hi:[1,0]
	v_pk_mul_f32 v[104:105], v[104:105], v[124:125]
	v_cvt_pk_bf16_f32 v118, v104, v105
	v_pk_mul_f32 v[104:105], v[102:103], v[144:145] op_sel_hi:[1,0]
	v_pk_mul_f32 v[104:105], v[104:105], v[126:127]
	v_cvt_pk_bf16_f32 v119, v104, v105
	v_add_u32_e32 v138, 0x1000000, v135
	global_store_dwordx4 v138, v[116:119], s[34:35]
	v_add_u32_e32 v136, 0x1800000, v133
	v_add_u32_e32 v137, 0x5400000, v134
	global_load_dwordx4 v[48:51], v136, s[22:23] nt
	global_load_dwordx4 v[52:55], v136, s[20:21] nt
	global_load_dwordx4 v[56:59], v137, s[38:39] nt
	s_waitcnt vmcnt(26)
	v_lshlrev_b32_e32 v104, 16, v60
	v_and_b32_e32 v105, 0xffff0000, v60
	v_lshlrev_b32_e32 v106, 16, v64
	v_and_b32_e32 v107, 0xffff0000, v64
	v_lshlrev_b32_e32 v108, 16, v68
	v_and_b32_e32 v109, 0xffff0000, v68
	v_pk_add_f32 v[104:105], v[104:105], v[106:107]
	v_pk_mul_f32 v[110:111], v[108:109], v[108:109]
	v_pk_fma_f32 v[110:111], v[110:111], v[140:141], 1.0 op_sel_hi:[1,0,0]
	v_pk_mul_f32 v[110:111], v[110:111], v[108:109]
	v_pk_mul_f32 v[110:111], v[110:111], v[142:143] op_sel_hi:[1,0]
	v_exp_f32_e32 v110, v110
	v_exp_f32_e32 v111, v111
	s_nop 0
	v_pk_add_f32 v[110:111], v[110:111], 1.0 op_sel_hi:[1,0]
	v_rcp_f32_e32 v110, v110
	v_rcp_f32_e32 v111, v111
	s_nop 0
	v_pk_mul_f32 v[110:111], v[110:111], v[108:109]
	v_pk_mul_f32 v[96:97], v[104:105], v[110:111]
	v_pk_mul_f32 v[112:113], v[96:97], v[96:97]
	v_lshlrev_b32_e32 v104, 16, v61
	v_and_b32_e32 v105, 0xffff0000, v61
	v_lshlrev_b32_e32 v106, 16, v65
	v_and_b32_e32 v107, 0xffff0000, v65
	v_lshlrev_b32_e32 v108, 16, v69
	v_and_b32_e32 v109, 0xffff0000, v69
	v_pk_add_f32 v[104:105], v[104:105], v[106:107]
	v_pk_mul_f32 v[110:111], v[108:109], v[108:109]
	v_pk_fma_f32 v[110:111], v[110:111], v[140:141], 1.0 op_sel_hi:[1,0,0]
	v_pk_mul_f32 v[110:111], v[110:111], v[108:109]
	v_pk_mul_f32 v[110:111], v[110:111], v[142:143] op_sel_hi:[1,0]
	v_exp_f32_e32 v110, v110
	v_exp_f32_e32 v111, v111
	s_nop 0
	v_pk_add_f32 v[110:111], v[110:111], 1.0 op_sel_hi:[1,0]
	v_rcp_f32_e32 v110, v110
	v_rcp_f32_e32 v111, v111
	s_nop 0
	v_pk_mul_f32 v[110:111], v[110:111], v[108:109]
	v_pk_mul_f32 v[98:99], v[104:105], v[110:111]
	v_pk_fma_f32 v[112:113], v[98:99], v[98:99], v[112:113]
	v_lshlrev_b32_e32 v104, 16, v62
	v_and_b32_e32 v105, 0xffff0000, v62
	v_lshlrev_b32_e32 v106, 16, v66
	v_and_b32_e32 v107, 0xffff0000, v66
	v_lshlrev_b32_e32 v108, 16, v70
	v_and_b32_e32 v109, 0xffff0000, v70
	v_pk_add_f32 v[104:105], v[104:105], v[106:107]
	v_pk_mul_f32 v[110:111], v[108:109], v[108:109]
	v_pk_fma_f32 v[110:111], v[110:111], v[140:141], 1.0 op_sel_hi:[1,0,0]
	v_pk_mul_f32 v[110:111], v[110:111], v[108:109]
	v_pk_mul_f32 v[110:111], v[110:111], v[142:143] op_sel_hi:[1,0]
	v_exp_f32_e32 v110, v110
	v_exp_f32_e32 v111, v111
	s_nop 0
	v_pk_add_f32 v[110:111], v[110:111], 1.0 op_sel_hi:[1,0]
	v_rcp_f32_e32 v110, v110
	v_rcp_f32_e32 v111, v111
	s_nop 0
	v_pk_mul_f32 v[110:111], v[110:111], v[108:109]
	v_pk_mul_f32 v[100:101], v[104:105], v[110:111]
	v_pk_fma_f32 v[112:113], v[100:101], v[100:101], v[112:113]
	v_lshlrev_b32_e32 v104, 16, v63
	v_and_b32_e32 v105, 0xffff0000, v63
	v_lshlrev_b32_e32 v106, 16, v67
	v_and_b32_e32 v107, 0xffff0000, v67
	v_lshlrev_b32_e32 v108, 16, v71
	v_and_b32_e32 v109, 0xffff0000, v71
	v_pk_add_f32 v[104:105], v[104:105], v[106:107]
	v_pk_mul_f32 v[110:111], v[108:109], v[108:109]
	v_pk_fma_f32 v[110:111], v[110:111], v[140:141], 1.0 op_sel_hi:[1,0,0]
	v_pk_mul_f32 v[110:111], v[110:111], v[108:109]
	v_pk_mul_f32 v[110:111], v[110:111], v[142:143] op_sel_hi:[1,0]
	v_exp_f32_e32 v110, v110
	v_exp_f32_e32 v111, v111
	s_nop 0
	v_pk_add_f32 v[110:111], v[110:111], 1.0 op_sel_hi:[1,0]
	v_rcp_f32_e32 v110, v110
	v_rcp_f32_e32 v111, v111
	s_nop 0
	v_pk_mul_f32 v[110:111], v[110:111], v[108:109]
	v_pk_mul_f32 v[102:103], v[104:105], v[110:111]
	v_pk_fma_f32 v[112:113], v[102:103], v[102:103], v[112:113]
	v_add_f32_e32 v112, v112, v113
	s_nop 1
	v_add_f32_dpp v112, v112, v112 quad_perm:[1,0,3,2] row_mask:0xf bank_mask:0xf
	s_nop 1
	v_add_f32_dpp v112, v112, v112 quad_perm:[2,3,0,1] row_mask:0xf bank_mask:0xf
	s_nop 1
	v_add_f32_dpp v112, v112, v112 row_half_mirror row_mask:0xf bank_mask:0xf
	s_nop 1
	v_add_f32_dpp v112, v112, v112 row_mirror row_mask:0xf bank_mask:0xf
	s_nop 1
	v_readlane_b32 s98, v112, 0
	v_readlane_b32 s99, v112, 16
	v_readlane_b32 s100, v112, 32
	v_readlane_b32 vcc_lo, v112, 48
	s_nop 1
	v_mov_b32_e32 v113, s98
	v_add_f32_e32 v113, s99, v113
	v_add_f32_e32 v113, s100, v113
	v_add_f32_e32 v113, vcc_lo, v113
	v_fmamk_f32 v144, v113, 0x3b000000, v131
	v_rsq_f32_e32 v144, v144
	s_nop 0
	v_pk_mul_f32 v[104:105], v[96:97], v[144:145] op_sel_hi:[1,0]
	v_pk_mul_f32 v[104:105], v[104:105], v[120:121]
	v_cvt_pk_bf16_f32 v116, v104, v105
	v_pk_mul_f32 v[104:105], v[98:99], v[144:145] op_sel_hi:[1,0]
	v_pk_mul_f32 v[104:105], v[104:105], v[122:123]
	v_cvt_pk_bf16_f32 v117, v104, v105
	v_pk_mul_f32 v[104:105], v[100:101], v[144:145] op_sel_hi:[1,0]
	v_pk_mul_f32 v[104:105], v[104:105], v[124:125]
	v_cvt_pk_bf16_f32 v118, v104, v105
	v_pk_mul_f32 v[104:105], v[102:103], v[144:145] op_sel_hi:[1,0]
	v_pk_mul_f32 v[104:105], v[104:105], v[126:127]
	v_cvt_pk_bf16_f32 v119, v104, v105
	v_add_u32_e32 v138, 0x1400000, v135
	global_store_dwordx4 v138, v[116:119], s[34:35]
	v_add_u32_e32 v136, 0x1a00000, v133
	v_add_u32_e32 v137, 0x5b00000, v134
	global_load_dwordx4 v[60:63], v136, s[22:23] nt
	global_load_dwordx4 v[64:67], v136, s[20:21] nt
	global_load_dwordx4 v[68:71], v137, s[38:39] nt
	s_waitcnt vmcnt(27)
	v_lshlrev_b32_e32 v104, 16, v72
	v_and_b32_e32 v105, 0xffff0000, v72
	v_lshlrev_b32_e32 v106, 16, v76
	v_and_b32_e32 v107, 0xffff0000, v76
	v_lshlrev_b32_e32 v108, 16, v80
	v_and_b32_e32 v109, 0xffff0000, v80
	v_pk_add_f32 v[104:105], v[104:105], v[106:107]
	v_pk_mul_f32 v[110:111], v[108:109], v[108:109]
	v_pk_fma_f32 v[110:111], v[110:111], v[140:141], 1.0 op_sel_hi:[1,0,0]
	v_pk_mul_f32 v[110:111], v[110:111], v[108:109]
	v_pk_mul_f32 v[110:111], v[110:111], v[142:143] op_sel_hi:[1,0]
	v_exp_f32_e32 v110, v110
	v_exp_f32_e32 v111, v111
	s_nop 0
	v_pk_add_f32 v[110:111], v[110:111], 1.0 op_sel_hi:[1,0]
	v_rcp_f32_e32 v110, v110
	v_rcp_f32_e32 v111, v111
	s_nop 0
	v_pk_mul_f32 v[110:111], v[110:111], v[108:109]
	v_pk_mul_f32 v[96:97], v[104:105], v[110:111]
	v_pk_mul_f32 v[112:113], v[96:97], v[96:97]
	v_lshlrev_b32_e32 v104, 16, v73
	v_and_b32_e32 v105, 0xffff0000, v73
	v_lshlrev_b32_e32 v106, 16, v77
	v_and_b32_e32 v107, 0xffff0000, v77
	v_lshlrev_b32_e32 v108, 16, v81
	v_and_b32_e32 v109, 0xffff0000, v81
	v_pk_add_f32 v[104:105], v[104:105], v[106:107]
	v_pk_mul_f32 v[110:111], v[108:109], v[108:109]
	v_pk_fma_f32 v[110:111], v[110:111], v[140:141], 1.0 op_sel_hi:[1,0,0]
	v_pk_mul_f32 v[110:111], v[110:111], v[108:109]
	v_pk_mul_f32 v[110:111], v[110:111], v[142:143] op_sel_hi:[1,0]
	v_exp_f32_e32 v110, v110
	v_exp_f32_e32 v111, v111
	s_nop 0
	v_pk_add_f32 v[110:111], v[110:111], 1.0 op_sel_hi:[1,0]
	v_rcp_f32_e32 v110, v110
	v_rcp_f32_e32 v111, v111
	s_nop 0
	v_pk_mul_f32 v[110:111], v[110:111], v[108:109]
	v_pk_mul_f32 v[98:99], v[104:105], v[110:111]
	v_pk_fma_f32 v[112:113], v[98:99], v[98:99], v[112:113]
	v_lshlrev_b32_e32 v104, 16, v74
	v_and_b32_e32 v105, 0xffff0000, v74
	v_lshlrev_b32_e32 v106, 16, v78
	v_and_b32_e32 v107, 0xffff0000, v78
	v_lshlrev_b32_e32 v108, 16, v82
	v_and_b32_e32 v109, 0xffff0000, v82
	v_pk_add_f32 v[104:105], v[104:105], v[106:107]
	v_pk_mul_f32 v[110:111], v[108:109], v[108:109]
	v_pk_fma_f32 v[110:111], v[110:111], v[140:141], 1.0 op_sel_hi:[1,0,0]
	v_pk_mul_f32 v[110:111], v[110:111], v[108:109]
	v_pk_mul_f32 v[110:111], v[110:111], v[142:143] op_sel_hi:[1,0]
	v_exp_f32_e32 v110, v110
	v_exp_f32_e32 v111, v111
	s_nop 0
	v_pk_add_f32 v[110:111], v[110:111], 1.0 op_sel_hi:[1,0]
	v_rcp_f32_e32 v110, v110
	v_rcp_f32_e32 v111, v111
	s_nop 0
	v_pk_mul_f32 v[110:111], v[110:111], v[108:109]
	v_pk_mul_f32 v[100:101], v[104:105], v[110:111]
	v_pk_fma_f32 v[112:113], v[100:101], v[100:101], v[112:113]
	v_lshlrev_b32_e32 v104, 16, v75
	v_and_b32_e32 v105, 0xffff0000, v75
	v_lshlrev_b32_e32 v106, 16, v79
	v_and_b32_e32 v107, 0xffff0000, v79
	v_lshlrev_b32_e32 v108, 16, v83
	v_and_b32_e32 v109, 0xffff0000, v83
	v_pk_add_f32 v[104:105], v[104:105], v[106:107]
	v_pk_mul_f32 v[110:111], v[108:109], v[108:109]
	v_pk_fma_f32 v[110:111], v[110:111], v[140:141], 1.0 op_sel_hi:[1,0,0]
	v_pk_mul_f32 v[110:111], v[110:111], v[108:109]
	v_pk_mul_f32 v[110:111], v[110:111], v[142:143] op_sel_hi:[1,0]
	v_exp_f32_e32 v110, v110
	v_exp_f32_e32 v111, v111
	s_nop 0
	v_pk_add_f32 v[110:111], v[110:111], 1.0 op_sel_hi:[1,0]
	v_rcp_f32_e32 v110, v110
	v_rcp_f32_e32 v111, v111
	s_nop 0
	v_pk_mul_f32 v[110:111], v[110:111], v[108:109]
	v_pk_mul_f32 v[102:103], v[104:105], v[110:111]
	v_pk_fma_f32 v[112:113], v[102:103], v[102:103], v[112:113]
	v_add_f32_e32 v112, v112, v113
	s_nop 1
	v_add_f32_dpp v112, v112, v112 quad_perm:[1,0,3,2] row_mask:0xf bank_mask:0xf
	s_nop 1
	v_add_f32_dpp v112, v112, v112 quad_perm:[2,3,0,1] row_mask:0xf bank_mask:0xf
	s_nop 1
	v_add_f32_dpp v112, v112, v112 row_half_mirror row_mask:0xf bank_mask:0xf
	s_nop 1
	v_add_f32_dpp v112, v112, v112 row_mirror row_mask:0xf bank_mask:0xf
	s_nop 1
	v_readlane_b32 s98, v112, 0
	v_readlane_b32 s99, v112, 16
	v_readlane_b32 s100, v112, 32
	v_readlane_b32 vcc_lo, v112, 48
	s_nop 1
	v_mov_b32_e32 v113, s98
	v_add_f32_e32 v113, s99, v113
	v_add_f32_e32 v113, s100, v113
	v_add_f32_e32 v113, vcc_lo, v113
	v_fmamk_f32 v144, v113, 0x3b000000, v131
	v_rsq_f32_e32 v144, v144
	s_nop 0
	v_pk_mul_f32 v[104:105], v[96:97], v[144:145] op_sel_hi:[1,0]
	v_pk_mul_f32 v[104:105], v[104:105], v[120:121]
	v_cvt_pk_bf16_f32 v116, v104, v105
	v_pk_mul_f32 v[104:105], v[98:99], v[144:145] op_sel_hi:[1,0]
	v_pk_mul_f32 v[104:105], v[104:105], v[122:123]
	v_cvt_pk_bf16_f32 v117, v104, v105
	v_pk_mul_f32 v[104:105], v[100:101], v[144:145] op_sel_hi:[1,0]
	v_pk_mul_f32 v[104:105], v[104:105], v[124:125]
	v_cvt_pk_bf16_f32 v118, v104, v105
	v_pk_mul_f32 v[104:105], v[102:103], v[144:145] op_sel_hi:[1,0]
	v_pk_mul_f32 v[104:105], v[104:105], v[126:127]
	v_cvt_pk_bf16_f32 v119, v104, v105
	v_add_u32_e32 v138, 0x1800000, v135
	global_store_dwordx4 v138, v[116:119], s[34:35]
	v_add_u32_e32 v136, 0x1c00000, v133
	v_add_u32_e32 v137, 0x6200000, v134
	global_load_dwordx4 v[72:75], v136, s[22:23] nt
	global_load_dwordx4 v[76:79], v136, s[20:21] nt
	global_load_dwordx4 v[80:83], v137, s[38:39] nt
	s_waitcnt vmcnt(28)
	v_lshlrev_b32_e32 v104, 16, v84
	v_and_b32_e32 v105, 0xffff0000, v84
	v_lshlrev_b32_e32 v106, 16, v88
	v_and_b32_e32 v107, 0xffff0000, v88
	v_lshlrev_b32_e32 v108, 16, v92
	v_and_b32_e32 v109, 0xffff0000, v92
	v_pk_add_f32 v[104:105], v[104:105], v[106:107]
	v_pk_mul_f32 v[110:111], v[108:109], v[108:109]
	v_pk_fma_f32 v[110:111], v[110:111], v[140:141], 1.0 op_sel_hi:[1,0,0]
	v_pk_mul_f32 v[110:111], v[110:111], v[108:109]
	v_pk_mul_f32 v[110:111], v[110:111], v[142:143] op_sel_hi:[1,0]
	v_exp_f32_e32 v110, v110
	v_exp_f32_e32 v111, v111
	s_nop 0
	v_pk_add_f32 v[110:111], v[110:111], 1.0 op_sel_hi:[1,0]
	v_rcp_f32_e32 v110, v110
	v_rcp_f32_e32 v111, v111
	s_nop 0
	v_pk_mul_f32 v[110:111], v[110:111], v[108:109]
	v_pk_mul_f32 v[96:97], v[104:105], v[110:111]
	v_pk_mul_f32 v[112:113], v[96:97], v[96:97]
	v_lshlrev_b32_e32 v104, 16, v85
	v_and_b32_e32 v105, 0xffff0000, v85
	v_lshlrev_b32_e32 v106, 16, v89
	v_and_b32_e32 v107, 0xffff0000, v89
	v_lshlrev_b32_e32 v108, 16, v93
	v_and_b32_e32 v109, 0xffff0000, v93
	v_pk_add_f32 v[104:105], v[104:105], v[106:107]
	v_pk_mul_f32 v[110:111], v[108:109], v[108:109]
	v_pk_fma_f32 v[110:111], v[110:111], v[140:141], 1.0 op_sel_hi:[1,0,0]
	v_pk_mul_f32 v[110:111], v[110:111], v[108:109]
	v_pk_mul_f32 v[110:111], v[110:111], v[142:143] op_sel_hi:[1,0]
	v_exp_f32_e32 v110, v110
	v_exp_f32_e32 v111, v111
	s_nop 0
	v_pk_add_f32 v[110:111], v[110:111], 1.0 op_sel_hi:[1,0]
	v_rcp_f32_e32 v110, v110
	v_rcp_f32_e32 v111, v111
	s_nop 0
	v_pk_mul_f32 v[110:111], v[110:111], v[108:109]
	v_pk_mul_f32 v[98:99], v[104:105], v[110:111]
	v_pk_fma_f32 v[112:113], v[98:99], v[98:99], v[112:113]
	v_lshlrev_b32_e32 v104, 16, v86
	v_and_b32_e32 v105, 0xffff0000, v86
	v_lshlrev_b32_e32 v106, 16, v90
	v_and_b32_e32 v107, 0xffff0000, v90
	v_lshlrev_b32_e32 v108, 16, v94
	v_and_b32_e32 v109, 0xffff0000, v94
	v_pk_add_f32 v[104:105], v[104:105], v[106:107]
	v_pk_mul_f32 v[110:111], v[108:109], v[108:109]
	v_pk_fma_f32 v[110:111], v[110:111], v[140:141], 1.0 op_sel_hi:[1,0,0]
	v_pk_mul_f32 v[110:111], v[110:111], v[108:109]
	v_pk_mul_f32 v[110:111], v[110:111], v[142:143] op_sel_hi:[1,0]
	v_exp_f32_e32 v110, v110
	v_exp_f32_e32 v111, v111
	s_nop 0
	v_pk_add_f32 v[110:111], v[110:111], 1.0 op_sel_hi:[1,0]
	v_rcp_f32_e32 v110, v110
	v_rcp_f32_e32 v111, v111
	s_nop 0
	v_pk_mul_f32 v[110:111], v[110:111], v[108:109]
	v_pk_mul_f32 v[100:101], v[104:105], v[110:111]
	v_pk_fma_f32 v[112:113], v[100:101], v[100:101], v[112:113]
	v_lshlrev_b32_e32 v104, 16, v87
	v_and_b32_e32 v105, 0xffff0000, v87
	v_lshlrev_b32_e32 v106, 16, v91
	v_and_b32_e32 v107, 0xffff0000, v91
	v_lshlrev_b32_e32 v108, 16, v95
	v_and_b32_e32 v109, 0xffff0000, v95
	v_pk_add_f32 v[104:105], v[104:105], v[106:107]
	v_pk_mul_f32 v[110:111], v[108:109], v[108:109]
	v_pk_fma_f32 v[110:111], v[110:111], v[140:141], 1.0 op_sel_hi:[1,0,0]
	v_pk_mul_f32 v[110:111], v[110:111], v[108:109]
	v_pk_mul_f32 v[110:111], v[110:111], v[142:143] op_sel_hi:[1,0]
	v_exp_f32_e32 v110, v110
	v_exp_f32_e32 v111, v111
	s_nop 0
	v_pk_add_f32 v[110:111], v[110:111], 1.0 op_sel_hi:[1,0]
	v_rcp_f32_e32 v110, v110
	v_rcp_f32_e32 v111, v111
	s_nop 0
	v_pk_mul_f32 v[110:111], v[110:111], v[108:109]
	v_pk_mul_f32 v[102:103], v[104:105], v[110:111]
	v_pk_fma_f32 v[112:113], v[102:103], v[102:103], v[112:113]
	v_add_f32_e32 v112, v112, v113
	s_nop 1
	v_add_f32_dpp v112, v112, v112 quad_perm:[1,0,3,2] row_mask:0xf bank_mask:0xf
	s_nop 1
	v_add_f32_dpp v112, v112, v112 quad_perm:[2,3,0,1] row_mask:0xf bank_mask:0xf
	s_nop 1
	v_add_f32_dpp v112, v112, v112 row_half_mirror row_mask:0xf bank_mask:0xf
	s_nop 1
	v_add_f32_dpp v112, v112, v112 row_mirror row_mask:0xf bank_mask:0xf
	s_nop 1
	v_readlane_b32 s98, v112, 0
	v_readlane_b32 s99, v112, 16
	v_readlane_b32 s100, v112, 32
	v_readlane_b32 vcc_lo, v112, 48
	s_nop 1
	v_mov_b32_e32 v113, s98
	v_add_f32_e32 v113, s99, v113
	v_add_f32_e32 v113, s100, v113
	v_add_f32_e32 v113, vcc_lo, v113
	v_fmamk_f32 v144, v113, 0x3b000000, v131
	v_rsq_f32_e32 v144, v144
	s_nop 0
	v_pk_mul_f32 v[104:105], v[96:97], v[144:145] op_sel_hi:[1,0]
	v_pk_mul_f32 v[104:105], v[104:105], v[120:121]
	v_cvt_pk_bf16_f32 v116, v104, v105
	v_pk_mul_f32 v[104:105], v[98:99], v[144:145] op_sel_hi:[1,0]
	v_pk_mul_f32 v[104:105], v[104:105], v[122:123]
	v_cvt_pk_bf16_f32 v117, v104, v105
	v_pk_mul_f32 v[104:105], v[100:101], v[144:145] op_sel_hi:[1,0]
	v_pk_mul_f32 v[104:105], v[104:105], v[124:125]
	v_cvt_pk_bf16_f32 v118, v104, v105
	v_pk_mul_f32 v[104:105], v[102:103], v[144:145] op_sel_hi:[1,0]
	v_pk_mul_f32 v[104:105], v[104:105], v[126:127]
	v_cvt_pk_bf16_f32 v119, v104, v105
	v_add_u32_e32 v138, 0x1c00000, v135
	global_store_dwordx4 v138, v[116:119], s[34:35]
	v_add_u32_e32 v136, 0x1e00000, v133
	v_add_u32_e32 v137, 0x6900000, v134
	global_load_dwordx4 v[84:87], v136, s[22:23] nt
	global_load_dwordx4 v[88:91], v136, s[20:21] nt
	global_load_dwordx4 v[92:95], v137, s[38:39] nt
	s_waitcnt vmcnt(28)
	v_lshlrev_b32_e32 v104, 16, v0
	v_and_b32_e32 v105, 0xffff0000, v0
	v_lshlrev_b32_e32 v106, 16, v4
	v_and_b32_e32 v107, 0xffff0000, v4
	v_lshlrev_b32_e32 v108, 16, v8
	v_and_b32_e32 v109, 0xffff0000, v8
	v_pk_add_f32 v[104:105], v[104:105], v[106:107]
	v_pk_mul_f32 v[110:111], v[108:109], v[108:109]
	v_pk_fma_f32 v[110:111], v[110:111], v[140:141], 1.0 op_sel_hi:[1,0,0]
	v_pk_mul_f32 v[110:111], v[110:111], v[108:109]
	v_pk_mul_f32 v[110:111], v[110:111], v[142:143] op_sel_hi:[1,0]
	v_exp_f32_e32 v110, v110
	v_exp_f32_e32 v111, v111
	s_nop 0
	v_pk_add_f32 v[110:111], v[110:111], 1.0 op_sel_hi:[1,0]
	v_rcp_f32_e32 v110, v110
	v_rcp_f32_e32 v111, v111
	s_nop 0
	v_pk_mul_f32 v[110:111], v[110:111], v[108:109]
	v_pk_mul_f32 v[96:97], v[104:105], v[110:111]
	v_pk_mul_f32 v[112:113], v[96:97], v[96:97]
	v_lshlrev_b32_e32 v104, 16, v1
	v_and_b32_e32 v105, 0xffff0000, v1
	v_lshlrev_b32_e32 v106, 16, v5
	v_and_b32_e32 v107, 0xffff0000, v5
	v_lshlrev_b32_e32 v108, 16, v9
	v_and_b32_e32 v109, 0xffff0000, v9
	v_pk_add_f32 v[104:105], v[104:105], v[106:107]
	v_pk_mul_f32 v[110:111], v[108:109], v[108:109]
	v_pk_fma_f32 v[110:111], v[110:111], v[140:141], 1.0 op_sel_hi:[1,0,0]
	v_pk_mul_f32 v[110:111], v[110:111], v[108:109]
	v_pk_mul_f32 v[110:111], v[110:111], v[142:143] op_sel_hi:[1,0]
	v_exp_f32_e32 v110, v110
	v_exp_f32_e32 v111, v111
	s_nop 0
	v_pk_add_f32 v[110:111], v[110:111], 1.0 op_sel_hi:[1,0]
	v_rcp_f32_e32 v110, v110
	v_rcp_f32_e32 v111, v111
	s_nop 0
	v_pk_mul_f32 v[110:111], v[110:111], v[108:109]
	v_pk_mul_f32 v[98:99], v[104:105], v[110:111]
	v_pk_fma_f32 v[112:113], v[98:99], v[98:99], v[112:113]
	v_lshlrev_b32_e32 v104, 16, v2
	v_and_b32_e32 v105, 0xffff0000, v2
	v_lshlrev_b32_e32 v106, 16, v6
	v_and_b32_e32 v107, 0xffff0000, v6
	v_lshlrev_b32_e32 v108, 16, v10
	v_and_b32_e32 v109, 0xffff0000, v10
	v_pk_add_f32 v[104:105], v[104:105], v[106:107]
	v_pk_mul_f32 v[110:111], v[108:109], v[108:109]
	v_pk_fma_f32 v[110:111], v[110:111], v[140:141], 1.0 op_sel_hi:[1,0,0]
	v_pk_mul_f32 v[110:111], v[110:111], v[108:109]
	v_pk_mul_f32 v[110:111], v[110:111], v[142:143] op_sel_hi:[1,0]
	v_exp_f32_e32 v110, v110
	v_exp_f32_e32 v111, v111
	s_nop 0
	v_pk_add_f32 v[110:111], v[110:111], 1.0 op_sel_hi:[1,0]
	v_rcp_f32_e32 v110, v110
	v_rcp_f32_e32 v111, v111
	s_nop 0
	v_pk_mul_f32 v[110:111], v[110:111], v[108:109]
	v_pk_mul_f32 v[100:101], v[104:105], v[110:111]
	v_pk_fma_f32 v[112:113], v[100:101], v[100:101], v[112:113]
	v_lshlrev_b32_e32 v104, 16, v3
	v_and_b32_e32 v105, 0xffff0000, v3
	v_lshlrev_b32_e32 v106, 16, v7
	v_and_b32_e32 v107, 0xffff0000, v7
	v_lshlrev_b32_e32 v108, 16, v11
	v_and_b32_e32 v109, 0xffff0000, v11
	v_pk_add_f32 v[104:105], v[104:105], v[106:107]
	v_pk_mul_f32 v[110:111], v[108:109], v[108:109]
	v_pk_fma_f32 v[110:111], v[110:111], v[140:141], 1.0 op_sel_hi:[1,0,0]
	v_pk_mul_f32 v[110:111], v[110:111], v[108:109]
	v_pk_mul_f32 v[110:111], v[110:111], v[142:143] op_sel_hi:[1,0]
	v_exp_f32_e32 v110, v110
	v_exp_f32_e32 v111, v111
	s_nop 0
	v_pk_add_f32 v[110:111], v[110:111], 1.0 op_sel_hi:[1,0]
	v_rcp_f32_e32 v110, v110
	v_rcp_f32_e32 v111, v111
	s_nop 0
	v_pk_mul_f32 v[110:111], v[110:111], v[108:109]
	v_pk_mul_f32 v[102:103], v[104:105], v[110:111]
	v_pk_fma_f32 v[112:113], v[102:103], v[102:103], v[112:113]
	v_add_f32_e32 v112, v112, v113
	s_nop 1
	v_add_f32_dpp v112, v112, v112 quad_perm:[1,0,3,2] row_mask:0xf bank_mask:0xf
	s_nop 1
	v_add_f32_dpp v112, v112, v112 quad_perm:[2,3,0,1] row_mask:0xf bank_mask:0xf
	s_nop 1
	v_add_f32_dpp v112, v112, v112 row_half_mirror row_mask:0xf bank_mask:0xf
	s_nop 1
	v_add_f32_dpp v112, v112, v112 row_mirror row_mask:0xf bank_mask:0xf
	s_nop 1
	v_readlane_b32 s98, v112, 0
	v_readlane_b32 s99, v112, 16
	v_readlane_b32 s100, v112, 32
	v_readlane_b32 vcc_lo, v112, 48
	s_nop 1
	v_mov_b32_e32 v113, s98
	v_add_f32_e32 v113, s99, v113
	v_add_f32_e32 v113, s100, v113
	v_add_f32_e32 v113, vcc_lo, v113
	v_fmamk_f32 v144, v113, 0x3b000000, v131
	v_rsq_f32_e32 v144, v144
	s_nop 0
	v_pk_mul_f32 v[104:105], v[96:97], v[144:145] op_sel_hi:[1,0]
	v_pk_mul_f32 v[104:105], v[104:105], v[120:121]
	v_cvt_pk_bf16_f32 v116, v104, v105
	v_pk_mul_f32 v[104:105], v[98:99], v[144:145] op_sel_hi:[1,0]
	v_pk_mul_f32 v[104:105], v[104:105], v[122:123]
	v_cvt_pk_bf16_f32 v117, v104, v105
	v_pk_mul_f32 v[104:105], v[100:101], v[144:145] op_sel_hi:[1,0]
	v_pk_mul_f32 v[104:105], v[104:105], v[124:125]
	v_cvt_pk_bf16_f32 v118, v104, v105
	v_pk_mul_f32 v[104:105], v[102:103], v[144:145] op_sel_hi:[1,0]
	v_pk_mul_f32 v[104:105], v[104:105], v[126:127]
	v_cvt_pk_bf16_f32 v119, v104, v105
	v_add_u32_e32 v138, 0x2000000, v135
	global_store_dwordx4 v138, v[116:119], s[34:35]
	s_waitcnt vmcnt(25)
	v_lshlrev_b32_e32 v104, 16, v12
	v_and_b32_e32 v105, 0xffff0000, v12
	v_lshlrev_b32_e32 v106, 16, v16
	v_and_b32_e32 v107, 0xffff0000, v16
	v_lshlrev_b32_e32 v108, 16, v20
	v_and_b32_e32 v109, 0xffff0000, v20
	v_pk_add_f32 v[104:105], v[104:105], v[106:107]
	v_pk_mul_f32 v[110:111], v[108:109], v[108:109]
	v_pk_fma_f32 v[110:111], v[110:111], v[140:141], 1.0 op_sel_hi:[1,0,0]
	v_pk_mul_f32 v[110:111], v[110:111], v[108:109]
	v_pk_mul_f32 v[110:111], v[110:111], v[142:143] op_sel_hi:[1,0]
	v_exp_f32_e32 v110, v110
	v_exp_f32_e32 v111, v111
	s_nop 0
	v_pk_add_f32 v[110:111], v[110:111], 1.0 op_sel_hi:[1,0]
	v_rcp_f32_e32 v110, v110
	v_rcp_f32_e32 v111, v111
	s_nop 0
	v_pk_mul_f32 v[110:111], v[110:111], v[108:109]
	v_pk_mul_f32 v[96:97], v[104:105], v[110:111]
	v_pk_mul_f32 v[112:113], v[96:97], v[96:97]
	v_lshlrev_b32_e32 v104, 16, v13
	v_and_b32_e32 v105, 0xffff0000, v13
	v_lshlrev_b32_e32 v106, 16, v17
	v_and_b32_e32 v107, 0xffff0000, v17
	v_lshlrev_b32_e32 v108, 16, v21
	v_and_b32_e32 v109, 0xffff0000, v21
	v_pk_add_f32 v[104:105], v[104:105], v[106:107]
	v_pk_mul_f32 v[110:111], v[108:109], v[108:109]
	v_pk_fma_f32 v[110:111], v[110:111], v[140:141], 1.0 op_sel_hi:[1,0,0]
	v_pk_mul_f32 v[110:111], v[110:111], v[108:109]
	v_pk_mul_f32 v[110:111], v[110:111], v[142:143] op_sel_hi:[1,0]
	v_exp_f32_e32 v110, v110
	v_exp_f32_e32 v111, v111
	s_nop 0
	v_pk_add_f32 v[110:111], v[110:111], 1.0 op_sel_hi:[1,0]
	v_rcp_f32_e32 v110, v110
	v_rcp_f32_e32 v111, v111
	s_nop 0
	v_pk_mul_f32 v[110:111], v[110:111], v[108:109]
	v_pk_mul_f32 v[98:99], v[104:105], v[110:111]
	v_pk_fma_f32 v[112:113], v[98:99], v[98:99], v[112:113]
	v_lshlrev_b32_e32 v104, 16, v14
	v_and_b32_e32 v105, 0xffff0000, v14
	v_lshlrev_b32_e32 v106, 16, v18
	v_and_b32_e32 v107, 0xffff0000, v18
	v_lshlrev_b32_e32 v108, 16, v22
	v_and_b32_e32 v109, 0xffff0000, v22
	v_pk_add_f32 v[104:105], v[104:105], v[106:107]
	v_pk_mul_f32 v[110:111], v[108:109], v[108:109]
	v_pk_fma_f32 v[110:111], v[110:111], v[140:141], 1.0 op_sel_hi:[1,0,0]
	v_pk_mul_f32 v[110:111], v[110:111], v[108:109]
	v_pk_mul_f32 v[110:111], v[110:111], v[142:143] op_sel_hi:[1,0]
	v_exp_f32_e32 v110, v110
	v_exp_f32_e32 v111, v111
	s_nop 0
	v_pk_add_f32 v[110:111], v[110:111], 1.0 op_sel_hi:[1,0]
	v_rcp_f32_e32 v110, v110
	v_rcp_f32_e32 v111, v111
	s_nop 0
	v_pk_mul_f32 v[110:111], v[110:111], v[108:109]
	v_pk_mul_f32 v[100:101], v[104:105], v[110:111]
	v_pk_fma_f32 v[112:113], v[100:101], v[100:101], v[112:113]
	v_lshlrev_b32_e32 v104, 16, v15
	v_and_b32_e32 v105, 0xffff0000, v15
	v_lshlrev_b32_e32 v106, 16, v19
	v_and_b32_e32 v107, 0xffff0000, v19
	v_lshlrev_b32_e32 v108, 16, v23
	v_and_b32_e32 v109, 0xffff0000, v23
	v_pk_add_f32 v[104:105], v[104:105], v[106:107]
	v_pk_mul_f32 v[110:111], v[108:109], v[108:109]
	v_pk_fma_f32 v[110:111], v[110:111], v[140:141], 1.0 op_sel_hi:[1,0,0]
	v_pk_mul_f32 v[110:111], v[110:111], v[108:109]
	v_pk_mul_f32 v[110:111], v[110:111], v[142:143] op_sel_hi:[1,0]
	v_exp_f32_e32 v110, v110
	v_exp_f32_e32 v111, v111
	s_nop 0
	v_pk_add_f32 v[110:111], v[110:111], 1.0 op_sel_hi:[1,0]
	v_rcp_f32_e32 v110, v110
	v_rcp_f32_e32 v111, v111
	s_nop 0
	v_pk_mul_f32 v[110:111], v[110:111], v[108:109]
	v_pk_mul_f32 v[102:103], v[104:105], v[110:111]
	v_pk_fma_f32 v[112:113], v[102:103], v[102:103], v[112:113]
	v_add_f32_e32 v112, v112, v113
	s_nop 1
	v_add_f32_dpp v112, v112, v112 quad_perm:[1,0,3,2] row_mask:0xf bank_mask:0xf
	s_nop 1
	v_add_f32_dpp v112, v112, v112 quad_perm:[2,3,0,1] row_mask:0xf bank_mask:0xf
	s_nop 1
	v_add_f32_dpp v112, v112, v112 row_half_mirror row_mask:0xf bank_mask:0xf
	s_nop 1
	v_add_f32_dpp v112, v112, v112 row_mirror row_mask:0xf bank_mask:0xf
	s_nop 1
	v_readlane_b32 s98, v112, 0
	v_readlane_b32 s99, v112, 16
	v_readlane_b32 s100, v112, 32
	v_readlane_b32 vcc_lo, v112, 48
	s_nop 1
	v_mov_b32_e32 v113, s98
	v_add_f32_e32 v113, s99, v113
	v_add_f32_e32 v113, s100, v113
	v_add_f32_e32 v113, vcc_lo, v113
	v_fmamk_f32 v144, v113, 0x3b000000, v131
	v_rsq_f32_e32 v144, v144
	s_nop 0
	v_pk_mul_f32 v[104:105], v[96:97], v[144:145] op_sel_hi:[1,0]
	v_pk_mul_f32 v[104:105], v[104:105], v[120:121]
	v_cvt_pk_bf16_f32 v116, v104, v105
	v_pk_mul_f32 v[104:105], v[98:99], v[144:145] op_sel_hi:[1,0]
	v_pk_mul_f32 v[104:105], v[104:105], v[122:123]
	v_cvt_pk_bf16_f32 v117, v104, v105
	v_pk_mul_f32 v[104:105], v[100:101], v[144:145] op_sel_hi:[1,0]
	v_pk_mul_f32 v[104:105], v[104:105], v[124:125]
	v_cvt_pk_bf16_f32 v118, v104, v105
	v_pk_mul_f32 v[104:105], v[102:103], v[144:145] op_sel_hi:[1,0]
	v_pk_mul_f32 v[104:105], v[104:105], v[126:127]
	v_cvt_pk_bf16_f32 v119, v104, v105
	v_add_u32_e32 v138, 0x2400000, v135
	global_store_dwordx4 v138, v[116:119], s[34:35]
	s_waitcnt vmcnt(22)
	v_lshlrev_b32_e32 v104, 16, v24
	v_and_b32_e32 v105, 0xffff0000, v24
	v_lshlrev_b32_e32 v106, 16, v28
	v_and_b32_e32 v107, 0xffff0000, v28
	v_lshlrev_b32_e32 v108, 16, v32
	v_and_b32_e32 v109, 0xffff0000, v32
	v_pk_add_f32 v[104:105], v[104:105], v[106:107]
	v_pk_mul_f32 v[110:111], v[108:109], v[108:109]
	v_pk_fma_f32 v[110:111], v[110:111], v[140:141], 1.0 op_sel_hi:[1,0,0]
	v_pk_mul_f32 v[110:111], v[110:111], v[108:109]
	v_pk_mul_f32 v[110:111], v[110:111], v[142:143] op_sel_hi:[1,0]
	v_exp_f32_e32 v110, v110
	v_exp_f32_e32 v111, v111
	s_nop 0
	v_pk_add_f32 v[110:111], v[110:111], 1.0 op_sel_hi:[1,0]
	v_rcp_f32_e32 v110, v110
	v_rcp_f32_e32 v111, v111
	s_nop 0
	v_pk_mul_f32 v[110:111], v[110:111], v[108:109]
	v_pk_mul_f32 v[96:97], v[104:105], v[110:111]
	v_pk_mul_f32 v[112:113], v[96:97], v[96:97]
	v_lshlrev_b32_e32 v104, 16, v25
	v_and_b32_e32 v105, 0xffff0000, v25
	v_lshlrev_b32_e32 v106, 16, v29
	v_and_b32_e32 v107, 0xffff0000, v29
	v_lshlrev_b32_e32 v108, 16, v33
	v_and_b32_e32 v109, 0xffff0000, v33
	v_pk_add_f32 v[104:105], v[104:105], v[106:107]
	v_pk_mul_f32 v[110:111], v[108:109], v[108:109]
	v_pk_fma_f32 v[110:111], v[110:111], v[140:141], 1.0 op_sel_hi:[1,0,0]
	v_pk_mul_f32 v[110:111], v[110:111], v[108:109]
	v_pk_mul_f32 v[110:111], v[110:111], v[142:143] op_sel_hi:[1,0]
	v_exp_f32_e32 v110, v110
	v_exp_f32_e32 v111, v111
	s_nop 0
	v_pk_add_f32 v[110:111], v[110:111], 1.0 op_sel_hi:[1,0]
	v_rcp_f32_e32 v110, v110
	v_rcp_f32_e32 v111, v111
	s_nop 0
	v_pk_mul_f32 v[110:111], v[110:111], v[108:109]
	v_pk_mul_f32 v[98:99], v[104:105], v[110:111]
	v_pk_fma_f32 v[112:113], v[98:99], v[98:99], v[112:113]
	v_lshlrev_b32_e32 v104, 16, v26
	v_and_b32_e32 v105, 0xffff0000, v26
	v_lshlrev_b32_e32 v106, 16, v30
	v_and_b32_e32 v107, 0xffff0000, v30
	v_lshlrev_b32_e32 v108, 16, v34
	v_and_b32_e32 v109, 0xffff0000, v34
	v_pk_add_f32 v[104:105], v[104:105], v[106:107]
	v_pk_mul_f32 v[110:111], v[108:109], v[108:109]
	v_pk_fma_f32 v[110:111], v[110:111], v[140:141], 1.0 op_sel_hi:[1,0,0]
	v_pk_mul_f32 v[110:111], v[110:111], v[108:109]
	v_pk_mul_f32 v[110:111], v[110:111], v[142:143] op_sel_hi:[1,0]
	v_exp_f32_e32 v110, v110
	v_exp_f32_e32 v111, v111
	s_nop 0
	v_pk_add_f32 v[110:111], v[110:111], 1.0 op_sel_hi:[1,0]
	v_rcp_f32_e32 v110, v110
	v_rcp_f32_e32 v111, v111
	s_nop 0
	v_pk_mul_f32 v[110:111], v[110:111], v[108:109]
	v_pk_mul_f32 v[100:101], v[104:105], v[110:111]
	v_pk_fma_f32 v[112:113], v[100:101], v[100:101], v[112:113]
	v_lshlrev_b32_e32 v104, 16, v27
	v_and_b32_e32 v105, 0xffff0000, v27
	v_lshlrev_b32_e32 v106, 16, v31
	v_and_b32_e32 v107, 0xffff0000, v31
	v_lshlrev_b32_e32 v108, 16, v35
	v_and_b32_e32 v109, 0xffff0000, v35
	v_pk_add_f32 v[104:105], v[104:105], v[106:107]
	v_pk_mul_f32 v[110:111], v[108:109], v[108:109]
	v_pk_fma_f32 v[110:111], v[110:111], v[140:141], 1.0 op_sel_hi:[1,0,0]
	v_pk_mul_f32 v[110:111], v[110:111], v[108:109]
	v_pk_mul_f32 v[110:111], v[110:111], v[142:143] op_sel_hi:[1,0]
	v_exp_f32_e32 v110, v110
	v_exp_f32_e32 v111, v111
	s_nop 0
	v_pk_add_f32 v[110:111], v[110:111], 1.0 op_sel_hi:[1,0]
	v_rcp_f32_e32 v110, v110
	v_rcp_f32_e32 v111, v111
	s_nop 0
	v_pk_mul_f32 v[110:111], v[110:111], v[108:109]
	v_pk_mul_f32 v[102:103], v[104:105], v[110:111]
	v_pk_fma_f32 v[112:113], v[102:103], v[102:103], v[112:113]
	v_add_f32_e32 v112, v112, v113
	s_nop 1
	v_add_f32_dpp v112, v112, v112 quad_perm:[1,0,3,2] row_mask:0xf bank_mask:0xf
	s_nop 1
	v_add_f32_dpp v112, v112, v112 quad_perm:[2,3,0,1] row_mask:0xf bank_mask:0xf
	s_nop 1
	v_add_f32_dpp v112, v112, v112 row_half_mirror row_mask:0xf bank_mask:0xf
	s_nop 1
	v_add_f32_dpp v112, v112, v112 row_mirror row_mask:0xf bank_mask:0xf
	s_nop 1
	v_readlane_b32 s98, v112, 0
	v_readlane_b32 s99, v112, 16
	v_readlane_b32 s100, v112, 32
	v_readlane_b32 vcc_lo, v112, 48
	s_nop 1
	v_mov_b32_e32 v113, s98
	v_add_f32_e32 v113, s99, v113
	v_add_f32_e32 v113, s100, v113
	v_add_f32_e32 v113, vcc_lo, v113
	v_fmamk_f32 v144, v113, 0x3b000000, v131
	v_rsq_f32_e32 v144, v144
	s_nop 0
	v_pk_mul_f32 v[104:105], v[96:97], v[144:145] op_sel_hi:[1,0]
	v_pk_mul_f32 v[104:105], v[104:105], v[120:121]
	v_cvt_pk_bf16_f32 v116, v104, v105
	v_pk_mul_f32 v[104:105], v[98:99], v[144:145] op_sel_hi:[1,0]
	v_pk_mul_f32 v[104:105], v[104:105], v[122:123]
	v_cvt_pk_bf16_f32 v117, v104, v105
	v_pk_mul_f32 v[104:105], v[100:101], v[144:145] op_sel_hi:[1,0]
	v_pk_mul_f32 v[104:105], v[104:105], v[124:125]
	v_cvt_pk_bf16_f32 v118, v104, v105
	v_pk_mul_f32 v[104:105], v[102:103], v[144:145] op_sel_hi:[1,0]
	v_pk_mul_f32 v[104:105], v[104:105], v[126:127]
	v_cvt_pk_bf16_f32 v119, v104, v105
	v_add_u32_e32 v138, 0x2800000, v135
	global_store_dwordx4 v138, v[116:119], s[34:35]
	s_waitcnt vmcnt(19)
	v_lshlrev_b32_e32 v104, 16, v36
	v_and_b32_e32 v105, 0xffff0000, v36
	v_lshlrev_b32_e32 v106, 16, v40
	v_and_b32_e32 v107, 0xffff0000, v40
	v_lshlrev_b32_e32 v108, 16, v44
	v_and_b32_e32 v109, 0xffff0000, v44
	v_pk_add_f32 v[104:105], v[104:105], v[106:107]
	v_pk_mul_f32 v[110:111], v[108:109], v[108:109]
	v_pk_fma_f32 v[110:111], v[110:111], v[140:141], 1.0 op_sel_hi:[1,0,0]
	v_pk_mul_f32 v[110:111], v[110:111], v[108:109]
	v_pk_mul_f32 v[110:111], v[110:111], v[142:143] op_sel_hi:[1,0]
	v_exp_f32_e32 v110, v110
	v_exp_f32_e32 v111, v111
	s_nop 0
	v_pk_add_f32 v[110:111], v[110:111], 1.0 op_sel_hi:[1,0]
	v_rcp_f32_e32 v110, v110
	v_rcp_f32_e32 v111, v111
	s_nop 0
	v_pk_mul_f32 v[110:111], v[110:111], v[108:109]
	v_pk_mul_f32 v[96:97], v[104:105], v[110:111]
	v_pk_mul_f32 v[112:113], v[96:97], v[96:97]
	v_lshlrev_b32_e32 v104, 16, v37
	v_and_b32_e32 v105, 0xffff0000, v37
	v_lshlrev_b32_e32 v106, 16, v41
	v_and_b32_e32 v107, 0xffff0000, v41
	v_lshlrev_b32_e32 v108, 16, v45
	v_and_b32_e32 v109, 0xffff0000, v45
	v_pk_add_f32 v[104:105], v[104:105], v[106:107]
	v_pk_mul_f32 v[110:111], v[108:109], v[108:109]
	v_pk_fma_f32 v[110:111], v[110:111], v[140:141], 1.0 op_sel_hi:[1,0,0]
	v_pk_mul_f32 v[110:111], v[110:111], v[108:109]
	v_pk_mul_f32 v[110:111], v[110:111], v[142:143] op_sel_hi:[1,0]
	v_exp_f32_e32 v110, v110
	v_exp_f32_e32 v111, v111
	s_nop 0
	v_pk_add_f32 v[110:111], v[110:111], 1.0 op_sel_hi:[1,0]
	v_rcp_f32_e32 v110, v110
	v_rcp_f32_e32 v111, v111
	s_nop 0
	v_pk_mul_f32 v[110:111], v[110:111], v[108:109]
	v_pk_mul_f32 v[98:99], v[104:105], v[110:111]
	v_pk_fma_f32 v[112:113], v[98:99], v[98:99], v[112:113]
	v_lshlrev_b32_e32 v104, 16, v38
	v_and_b32_e32 v105, 0xffff0000, v38
	v_lshlrev_b32_e32 v106, 16, v42
	v_and_b32_e32 v107, 0xffff0000, v42
	v_lshlrev_b32_e32 v108, 16, v46
	v_and_b32_e32 v109, 0xffff0000, v46
	v_pk_add_f32 v[104:105], v[104:105], v[106:107]
	v_pk_mul_f32 v[110:111], v[108:109], v[108:109]
	v_pk_fma_f32 v[110:111], v[110:111], v[140:141], 1.0 op_sel_hi:[1,0,0]
	v_pk_mul_f32 v[110:111], v[110:111], v[108:109]
	v_pk_mul_f32 v[110:111], v[110:111], v[142:143] op_sel_hi:[1,0]
	v_exp_f32_e32 v110, v110
	v_exp_f32_e32 v111, v111
	s_nop 0
	v_pk_add_f32 v[110:111], v[110:111], 1.0 op_sel_hi:[1,0]
	v_rcp_f32_e32 v110, v110
	v_rcp_f32_e32 v111, v111
	s_nop 0
	v_pk_mul_f32 v[110:111], v[110:111], v[108:109]
	v_pk_mul_f32 v[100:101], v[104:105], v[110:111]
	v_pk_fma_f32 v[112:113], v[100:101], v[100:101], v[112:113]
	v_lshlrev_b32_e32 v104, 16, v39
	v_and_b32_e32 v105, 0xffff0000, v39
	v_lshlrev_b32_e32 v106, 16, v43
	v_and_b32_e32 v107, 0xffff0000, v43
	v_lshlrev_b32_e32 v108, 16, v47
	v_and_b32_e32 v109, 0xffff0000, v47
	v_pk_add_f32 v[104:105], v[104:105], v[106:107]
	v_pk_mul_f32 v[110:111], v[108:109], v[108:109]
	v_pk_fma_f32 v[110:111], v[110:111], v[140:141], 1.0 op_sel_hi:[1,0,0]
	v_pk_mul_f32 v[110:111], v[110:111], v[108:109]
	v_pk_mul_f32 v[110:111], v[110:111], v[142:143] op_sel_hi:[1,0]
	v_exp_f32_e32 v110, v110
	v_exp_f32_e32 v111, v111
	s_nop 0
	v_pk_add_f32 v[110:111], v[110:111], 1.0 op_sel_hi:[1,0]
	v_rcp_f32_e32 v110, v110
	v_rcp_f32_e32 v111, v111
	s_nop 0
	v_pk_mul_f32 v[110:111], v[110:111], v[108:109]
	v_pk_mul_f32 v[102:103], v[104:105], v[110:111]
	v_pk_fma_f32 v[112:113], v[102:103], v[102:103], v[112:113]
	v_add_f32_e32 v112, v112, v113
	s_nop 1
	v_add_f32_dpp v112, v112, v112 quad_perm:[1,0,3,2] row_mask:0xf bank_mask:0xf
	s_nop 1
	v_add_f32_dpp v112, v112, v112 quad_perm:[2,3,0,1] row_mask:0xf bank_mask:0xf
	s_nop 1
	v_add_f32_dpp v112, v112, v112 row_half_mirror row_mask:0xf bank_mask:0xf
	s_nop 1
	v_add_f32_dpp v112, v112, v112 row_mirror row_mask:0xf bank_mask:0xf
	s_nop 1
	v_readlane_b32 s98, v112, 0
	v_readlane_b32 s99, v112, 16
	v_readlane_b32 s100, v112, 32
	v_readlane_b32 vcc_lo, v112, 48
	s_nop 1
	v_mov_b32_e32 v113, s98
	v_add_f32_e32 v113, s99, v113
	v_add_f32_e32 v113, s100, v113
	v_add_f32_e32 v113, vcc_lo, v113
	v_fmamk_f32 v144, v113, 0x3b000000, v131
	v_rsq_f32_e32 v144, v144
	s_nop 0
	v_pk_mul_f32 v[104:105], v[96:97], v[144:145] op_sel_hi:[1,0]
	v_pk_mul_f32 v[104:105], v[104:105], v[120:121]
	v_cvt_pk_bf16_f32 v116, v104, v105
	v_pk_mul_f32 v[104:105], v[98:99], v[144:145] op_sel_hi:[1,0]
	v_pk_mul_f32 v[104:105], v[104:105], v[122:123]
	v_cvt_pk_bf16_f32 v117, v104, v105
	v_pk_mul_f32 v[104:105], v[100:101], v[144:145] op_sel_hi:[1,0]
	v_pk_mul_f32 v[104:105], v[104:105], v[124:125]
	v_cvt_pk_bf16_f32 v118, v104, v105
	v_pk_mul_f32 v[104:105], v[102:103], v[144:145] op_sel_hi:[1,0]
	v_pk_mul_f32 v[104:105], v[104:105], v[126:127]
	v_cvt_pk_bf16_f32 v119, v104, v105
	v_add_u32_e32 v138, 0x2c00000, v135
	global_store_dwordx4 v138, v[116:119], s[34:35]
	s_waitcnt vmcnt(16)
	v_lshlrev_b32_e32 v104, 16, v48
	v_and_b32_e32 v105, 0xffff0000, v48
	v_lshlrev_b32_e32 v106, 16, v52
	v_and_b32_e32 v107, 0xffff0000, v52
	v_lshlrev_b32_e32 v108, 16, v56
	v_and_b32_e32 v109, 0xffff0000, v56
	v_pk_add_f32 v[104:105], v[104:105], v[106:107]
	v_pk_mul_f32 v[110:111], v[108:109], v[108:109]
	v_pk_fma_f32 v[110:111], v[110:111], v[140:141], 1.0 op_sel_hi:[1,0,0]
	v_pk_mul_f32 v[110:111], v[110:111], v[108:109]
	v_pk_mul_f32 v[110:111], v[110:111], v[142:143] op_sel_hi:[1,0]
	v_exp_f32_e32 v110, v110
	v_exp_f32_e32 v111, v111
	s_nop 0
	v_pk_add_f32 v[110:111], v[110:111], 1.0 op_sel_hi:[1,0]
	v_rcp_f32_e32 v110, v110
	v_rcp_f32_e32 v111, v111
	s_nop 0
	v_pk_mul_f32 v[110:111], v[110:111], v[108:109]
	v_pk_mul_f32 v[96:97], v[104:105], v[110:111]
	v_pk_mul_f32 v[112:113], v[96:97], v[96:97]
	v_lshlrev_b32_e32 v104, 16, v49
	v_and_b32_e32 v105, 0xffff0000, v49
	v_lshlrev_b32_e32 v106, 16, v53
	v_and_b32_e32 v107, 0xffff0000, v53
	v_lshlrev_b32_e32 v108, 16, v57
	v_and_b32_e32 v109, 0xffff0000, v57
	v_pk_add_f32 v[104:105], v[104:105], v[106:107]
	v_pk_mul_f32 v[110:111], v[108:109], v[108:109]
	v_pk_fma_f32 v[110:111], v[110:111], v[140:141], 1.0 op_sel_hi:[1,0,0]
	v_pk_mul_f32 v[110:111], v[110:111], v[108:109]
	v_pk_mul_f32 v[110:111], v[110:111], v[142:143] op_sel_hi:[1,0]
	v_exp_f32_e32 v110, v110
	v_exp_f32_e32 v111, v111
	s_nop 0
	v_pk_add_f32 v[110:111], v[110:111], 1.0 op_sel_hi:[1,0]
	v_rcp_f32_e32 v110, v110
	v_rcp_f32_e32 v111, v111
	s_nop 0
	v_pk_mul_f32 v[110:111], v[110:111], v[108:109]
	v_pk_mul_f32 v[98:99], v[104:105], v[110:111]
	v_pk_fma_f32 v[112:113], v[98:99], v[98:99], v[112:113]
	v_lshlrev_b32_e32 v104, 16, v50
	v_and_b32_e32 v105, 0xffff0000, v50
	v_lshlrev_b32_e32 v106, 16, v54
	v_and_b32_e32 v107, 0xffff0000, v54
	v_lshlrev_b32_e32 v108, 16, v58
	v_and_b32_e32 v109, 0xffff0000, v58
	v_pk_add_f32 v[104:105], v[104:105], v[106:107]
	v_pk_mul_f32 v[110:111], v[108:109], v[108:109]
	v_pk_fma_f32 v[110:111], v[110:111], v[140:141], 1.0 op_sel_hi:[1,0,0]
	v_pk_mul_f32 v[110:111], v[110:111], v[108:109]
	v_pk_mul_f32 v[110:111], v[110:111], v[142:143] op_sel_hi:[1,0]
	v_exp_f32_e32 v110, v110
	v_exp_f32_e32 v111, v111
	s_nop 0
	v_pk_add_f32 v[110:111], v[110:111], 1.0 op_sel_hi:[1,0]
	v_rcp_f32_e32 v110, v110
	v_rcp_f32_e32 v111, v111
	s_nop 0
	v_pk_mul_f32 v[110:111], v[110:111], v[108:109]
	v_pk_mul_f32 v[100:101], v[104:105], v[110:111]
	v_pk_fma_f32 v[112:113], v[100:101], v[100:101], v[112:113]
	v_lshlrev_b32_e32 v104, 16, v51
	v_and_b32_e32 v105, 0xffff0000, v51
	v_lshlrev_b32_e32 v106, 16, v55
	v_and_b32_e32 v107, 0xffff0000, v55
	v_lshlrev_b32_e32 v108, 16, v59
	v_and_b32_e32 v109, 0xffff0000, v59
	v_pk_add_f32 v[104:105], v[104:105], v[106:107]
	v_pk_mul_f32 v[110:111], v[108:109], v[108:109]
	v_pk_fma_f32 v[110:111], v[110:111], v[140:141], 1.0 op_sel_hi:[1,0,0]
	v_pk_mul_f32 v[110:111], v[110:111], v[108:109]
	v_pk_mul_f32 v[110:111], v[110:111], v[142:143] op_sel_hi:[1,0]
	v_exp_f32_e32 v110, v110
	v_exp_f32_e32 v111, v111
	s_nop 0
	v_pk_add_f32 v[110:111], v[110:111], 1.0 op_sel_hi:[1,0]
	v_rcp_f32_e32 v110, v110
	v_rcp_f32_e32 v111, v111
	s_nop 0
	v_pk_mul_f32 v[110:111], v[110:111], v[108:109]
	v_pk_mul_f32 v[102:103], v[104:105], v[110:111]
	v_pk_fma_f32 v[112:113], v[102:103], v[102:103], v[112:113]
	v_add_f32_e32 v112, v112, v113
	s_nop 1
	v_add_f32_dpp v112, v112, v112 quad_perm:[1,0,3,2] row_mask:0xf bank_mask:0xf
	s_nop 1
	v_add_f32_dpp v112, v112, v112 quad_perm:[2,3,0,1] row_mask:0xf bank_mask:0xf
	s_nop 1
	v_add_f32_dpp v112, v112, v112 row_half_mirror row_mask:0xf bank_mask:0xf
	s_nop 1
	v_add_f32_dpp v112, v112, v112 row_mirror row_mask:0xf bank_mask:0xf
	s_nop 1
	v_readlane_b32 s98, v112, 0
	v_readlane_b32 s99, v112, 16
	v_readlane_b32 s100, v112, 32
	v_readlane_b32 vcc_lo, v112, 48
	s_nop 1
	v_mov_b32_e32 v113, s98
	v_add_f32_e32 v113, s99, v113
	v_add_f32_e32 v113, s100, v113
	v_add_f32_e32 v113, vcc_lo, v113
	v_fmamk_f32 v144, v113, 0x3b000000, v131
	v_rsq_f32_e32 v144, v144
	s_nop 0
	v_pk_mul_f32 v[104:105], v[96:97], v[144:145] op_sel_hi:[1,0]
	v_pk_mul_f32 v[104:105], v[104:105], v[120:121]
	v_cvt_pk_bf16_f32 v116, v104, v105
	v_pk_mul_f32 v[104:105], v[98:99], v[144:145] op_sel_hi:[1,0]
	v_pk_mul_f32 v[104:105], v[104:105], v[122:123]
	v_cvt_pk_bf16_f32 v117, v104, v105
	v_pk_mul_f32 v[104:105], v[100:101], v[144:145] op_sel_hi:[1,0]
	v_pk_mul_f32 v[104:105], v[104:105], v[124:125]
	v_cvt_pk_bf16_f32 v118, v104, v105
	v_pk_mul_f32 v[104:105], v[102:103], v[144:145] op_sel_hi:[1,0]
	v_pk_mul_f32 v[104:105], v[104:105], v[126:127]
	v_cvt_pk_bf16_f32 v119, v104, v105
	v_add_u32_e32 v138, 0x3000000, v135
	global_store_dwordx4 v138, v[116:119], s[34:35]
	s_waitcnt vmcnt(13)
	v_lshlrev_b32_e32 v104, 16, v60
	v_and_b32_e32 v105, 0xffff0000, v60
	v_lshlrev_b32_e32 v106, 16, v64
	v_and_b32_e32 v107, 0xffff0000, v64
	v_lshlrev_b32_e32 v108, 16, v68
	v_and_b32_e32 v109, 0xffff0000, v68
	v_pk_add_f32 v[104:105], v[104:105], v[106:107]
	v_pk_mul_f32 v[110:111], v[108:109], v[108:109]
	v_pk_fma_f32 v[110:111], v[110:111], v[140:141], 1.0 op_sel_hi:[1,0,0]
	v_pk_mul_f32 v[110:111], v[110:111], v[108:109]
	v_pk_mul_f32 v[110:111], v[110:111], v[142:143] op_sel_hi:[1,0]
	v_exp_f32_e32 v110, v110
	v_exp_f32_e32 v111, v111
	s_nop 0
	v_pk_add_f32 v[110:111], v[110:111], 1.0 op_sel_hi:[1,0]
	v_rcp_f32_e32 v110, v110
	v_rcp_f32_e32 v111, v111
	s_nop 0
	v_pk_mul_f32 v[110:111], v[110:111], v[108:109]
	v_pk_mul_f32 v[96:97], v[104:105], v[110:111]
	v_pk_mul_f32 v[112:113], v[96:97], v[96:97]
	v_lshlrev_b32_e32 v104, 16, v61
	v_and_b32_e32 v105, 0xffff0000, v61
	v_lshlrev_b32_e32 v106, 16, v65
	v_and_b32_e32 v107, 0xffff0000, v65
	v_lshlrev_b32_e32 v108, 16, v69
	v_and_b32_e32 v109, 0xffff0000, v69
	v_pk_add_f32 v[104:105], v[104:105], v[106:107]
	v_pk_mul_f32 v[110:111], v[108:109], v[108:109]
	v_pk_fma_f32 v[110:111], v[110:111], v[140:141], 1.0 op_sel_hi:[1,0,0]
	v_pk_mul_f32 v[110:111], v[110:111], v[108:109]
	v_pk_mul_f32 v[110:111], v[110:111], v[142:143] op_sel_hi:[1,0]
	v_exp_f32_e32 v110, v110
	v_exp_f32_e32 v111, v111
	s_nop 0
	v_pk_add_f32 v[110:111], v[110:111], 1.0 op_sel_hi:[1,0]
	v_rcp_f32_e32 v110, v110
	v_rcp_f32_e32 v111, v111
	s_nop 0
	v_pk_mul_f32 v[110:111], v[110:111], v[108:109]
	v_pk_mul_f32 v[98:99], v[104:105], v[110:111]
	v_pk_fma_f32 v[112:113], v[98:99], v[98:99], v[112:113]
	v_lshlrev_b32_e32 v104, 16, v62
	v_and_b32_e32 v105, 0xffff0000, v62
	v_lshlrev_b32_e32 v106, 16, v66
	v_and_b32_e32 v107, 0xffff0000, v66
	v_lshlrev_b32_e32 v108, 16, v70
	v_and_b32_e32 v109, 0xffff0000, v70
	v_pk_add_f32 v[104:105], v[104:105], v[106:107]
	v_pk_mul_f32 v[110:111], v[108:109], v[108:109]
	v_pk_fma_f32 v[110:111], v[110:111], v[140:141], 1.0 op_sel_hi:[1,0,0]
	v_pk_mul_f32 v[110:111], v[110:111], v[108:109]
	v_pk_mul_f32 v[110:111], v[110:111], v[142:143] op_sel_hi:[1,0]
	v_exp_f32_e32 v110, v110
	v_exp_f32_e32 v111, v111
	s_nop 0
	v_pk_add_f32 v[110:111], v[110:111], 1.0 op_sel_hi:[1,0]
	v_rcp_f32_e32 v110, v110
	v_rcp_f32_e32 v111, v111
	s_nop 0
	v_pk_mul_f32 v[110:111], v[110:111], v[108:109]
	v_pk_mul_f32 v[100:101], v[104:105], v[110:111]
	v_pk_fma_f32 v[112:113], v[100:101], v[100:101], v[112:113]
	v_lshlrev_b32_e32 v104, 16, v63
	v_and_b32_e32 v105, 0xffff0000, v63
	v_lshlrev_b32_e32 v106, 16, v67
	v_and_b32_e32 v107, 0xffff0000, v67
	v_lshlrev_b32_e32 v108, 16, v71
	v_and_b32_e32 v109, 0xffff0000, v71
	v_pk_add_f32 v[104:105], v[104:105], v[106:107]
	v_pk_mul_f32 v[110:111], v[108:109], v[108:109]
	v_pk_fma_f32 v[110:111], v[110:111], v[140:141], 1.0 op_sel_hi:[1,0,0]
	v_pk_mul_f32 v[110:111], v[110:111], v[108:109]
	v_pk_mul_f32 v[110:111], v[110:111], v[142:143] op_sel_hi:[1,0]
	v_exp_f32_e32 v110, v110
	v_exp_f32_e32 v111, v111
	s_nop 0
	v_pk_add_f32 v[110:111], v[110:111], 1.0 op_sel_hi:[1,0]
	v_rcp_f32_e32 v110, v110
	v_rcp_f32_e32 v111, v111
	s_nop 0
	v_pk_mul_f32 v[110:111], v[110:111], v[108:109]
	v_pk_mul_f32 v[102:103], v[104:105], v[110:111]
	v_pk_fma_f32 v[112:113], v[102:103], v[102:103], v[112:113]
	v_add_f32_e32 v112, v112, v113
	s_nop 1
	v_add_f32_dpp v112, v112, v112 quad_perm:[1,0,3,2] row_mask:0xf bank_mask:0xf
	s_nop 1
	v_add_f32_dpp v112, v112, v112 quad_perm:[2,3,0,1] row_mask:0xf bank_mask:0xf
	s_nop 1
	v_add_f32_dpp v112, v112, v112 row_half_mirror row_mask:0xf bank_mask:0xf
	s_nop 1
	v_add_f32_dpp v112, v112, v112 row_mirror row_mask:0xf bank_mask:0xf
	s_nop 1
	v_readlane_b32 s98, v112, 0
	v_readlane_b32 s99, v112, 16
	v_readlane_b32 s100, v112, 32
	v_readlane_b32 vcc_lo, v112, 48
	s_nop 1
	v_mov_b32_e32 v113, s98
	v_add_f32_e32 v113, s99, v113
	v_add_f32_e32 v113, s100, v113
	v_add_f32_e32 v113, vcc_lo, v113
	v_fmamk_f32 v144, v113, 0x3b000000, v131
	v_rsq_f32_e32 v144, v144
	s_nop 0
	v_pk_mul_f32 v[104:105], v[96:97], v[144:145] op_sel_hi:[1,0]
	v_pk_mul_f32 v[104:105], v[104:105], v[120:121]
	v_cvt_pk_bf16_f32 v116, v104, v105
	v_pk_mul_f32 v[104:105], v[98:99], v[144:145] op_sel_hi:[1,0]
	v_pk_mul_f32 v[104:105], v[104:105], v[122:123]
	v_cvt_pk_bf16_f32 v117, v104, v105
	v_pk_mul_f32 v[104:105], v[100:101], v[144:145] op_sel_hi:[1,0]
	v_pk_mul_f32 v[104:105], v[104:105], v[124:125]
	v_cvt_pk_bf16_f32 v118, v104, v105
	v_pk_mul_f32 v[104:105], v[102:103], v[144:145] op_sel_hi:[1,0]
	v_pk_mul_f32 v[104:105], v[104:105], v[126:127]
	v_cvt_pk_bf16_f32 v119, v104, v105
	v_add_u32_e32 v138, 0x3400000, v135
	global_store_dwordx4 v138, v[116:119], s[34:35]
	s_waitcnt vmcnt(10)
	v_lshlrev_b32_e32 v104, 16, v72
	v_and_b32_e32 v105, 0xffff0000, v72
	v_lshlrev_b32_e32 v106, 16, v76
	v_and_b32_e32 v107, 0xffff0000, v76
	v_lshlrev_b32_e32 v108, 16, v80
	v_and_b32_e32 v109, 0xffff0000, v80
	v_pk_add_f32 v[104:105], v[104:105], v[106:107]
	v_pk_mul_f32 v[110:111], v[108:109], v[108:109]
	v_pk_fma_f32 v[110:111], v[110:111], v[140:141], 1.0 op_sel_hi:[1,0,0]
	v_pk_mul_f32 v[110:111], v[110:111], v[108:109]
	v_pk_mul_f32 v[110:111], v[110:111], v[142:143] op_sel_hi:[1,0]
	v_exp_f32_e32 v110, v110
	v_exp_f32_e32 v111, v111
	s_nop 0
	v_pk_add_f32 v[110:111], v[110:111], 1.0 op_sel_hi:[1,0]
	v_rcp_f32_e32 v110, v110
	v_rcp_f32_e32 v111, v111
	s_nop 0
	v_pk_mul_f32 v[110:111], v[110:111], v[108:109]
	v_pk_mul_f32 v[96:97], v[104:105], v[110:111]
	v_pk_mul_f32 v[112:113], v[96:97], v[96:97]
	v_lshlrev_b32_e32 v104, 16, v73
	v_and_b32_e32 v105, 0xffff0000, v73
	v_lshlrev_b32_e32 v106, 16, v77
	v_and_b32_e32 v107, 0xffff0000, v77
	v_lshlrev_b32_e32 v108, 16, v81
	v_and_b32_e32 v109, 0xffff0000, v81
	v_pk_add_f32 v[104:105], v[104:105], v[106:107]
	v_pk_mul_f32 v[110:111], v[108:109], v[108:109]
	v_pk_fma_f32 v[110:111], v[110:111], v[140:141], 1.0 op_sel_hi:[1,0,0]
	v_pk_mul_f32 v[110:111], v[110:111], v[108:109]
	v_pk_mul_f32 v[110:111], v[110:111], v[142:143] op_sel_hi:[1,0]
	v_exp_f32_e32 v110, v110
	v_exp_f32_e32 v111, v111
	s_nop 0
	v_pk_add_f32 v[110:111], v[110:111], 1.0 op_sel_hi:[1,0]
	v_rcp_f32_e32 v110, v110
	v_rcp_f32_e32 v111, v111
	s_nop 0
	v_pk_mul_f32 v[110:111], v[110:111], v[108:109]
	v_pk_mul_f32 v[98:99], v[104:105], v[110:111]
	v_pk_fma_f32 v[112:113], v[98:99], v[98:99], v[112:113]
	v_lshlrev_b32_e32 v104, 16, v74
	v_and_b32_e32 v105, 0xffff0000, v74
	v_lshlrev_b32_e32 v106, 16, v78
	v_and_b32_e32 v107, 0xffff0000, v78
	v_lshlrev_b32_e32 v108, 16, v82
	v_and_b32_e32 v109, 0xffff0000, v82
	v_pk_add_f32 v[104:105], v[104:105], v[106:107]
	v_pk_mul_f32 v[110:111], v[108:109], v[108:109]
	v_pk_fma_f32 v[110:111], v[110:111], v[140:141], 1.0 op_sel_hi:[1,0,0]
	v_pk_mul_f32 v[110:111], v[110:111], v[108:109]
	v_pk_mul_f32 v[110:111], v[110:111], v[142:143] op_sel_hi:[1,0]
	v_exp_f32_e32 v110, v110
	v_exp_f32_e32 v111, v111
	s_nop 0
	v_pk_add_f32 v[110:111], v[110:111], 1.0 op_sel_hi:[1,0]
	v_rcp_f32_e32 v110, v110
	v_rcp_f32_e32 v111, v111
	s_nop 0
	v_pk_mul_f32 v[110:111], v[110:111], v[108:109]
	v_pk_mul_f32 v[100:101], v[104:105], v[110:111]
	v_pk_fma_f32 v[112:113], v[100:101], v[100:101], v[112:113]
	v_lshlrev_b32_e32 v104, 16, v75
	v_and_b32_e32 v105, 0xffff0000, v75
	v_lshlrev_b32_e32 v106, 16, v79
	v_and_b32_e32 v107, 0xffff0000, v79
	v_lshlrev_b32_e32 v108, 16, v83
	v_and_b32_e32 v109, 0xffff0000, v83
	v_pk_add_f32 v[104:105], v[104:105], v[106:107]
	v_pk_mul_f32 v[110:111], v[108:109], v[108:109]
	v_pk_fma_f32 v[110:111], v[110:111], v[140:141], 1.0 op_sel_hi:[1,0,0]
	v_pk_mul_f32 v[110:111], v[110:111], v[108:109]
	v_pk_mul_f32 v[110:111], v[110:111], v[142:143] op_sel_hi:[1,0]
	v_exp_f32_e32 v110, v110
	v_exp_f32_e32 v111, v111
	s_nop 0
	v_pk_add_f32 v[110:111], v[110:111], 1.0 op_sel_hi:[1,0]
	v_rcp_f32_e32 v110, v110
	v_rcp_f32_e32 v111, v111
	s_nop 0
	v_pk_mul_f32 v[110:111], v[110:111], v[108:109]
	v_pk_mul_f32 v[102:103], v[104:105], v[110:111]
	v_pk_fma_f32 v[112:113], v[102:103], v[102:103], v[112:113]
	v_add_f32_e32 v112, v112, v113
	s_nop 1
	v_add_f32_dpp v112, v112, v112 quad_perm:[1,0,3,2] row_mask:0xf bank_mask:0xf
	s_nop 1
	v_add_f32_dpp v112, v112, v112 quad_perm:[2,3,0,1] row_mask:0xf bank_mask:0xf
	s_nop 1
	v_add_f32_dpp v112, v112, v112 row_half_mirror row_mask:0xf bank_mask:0xf
	s_nop 1
	v_add_f32_dpp v112, v112, v112 row_mirror row_mask:0xf bank_mask:0xf
	s_nop 1
	v_readlane_b32 s98, v112, 0
	v_readlane_b32 s99, v112, 16
	v_readlane_b32 s100, v112, 32
	v_readlane_b32 vcc_lo, v112, 48
	s_nop 1
	v_mov_b32_e32 v113, s98
	v_add_f32_e32 v113, s99, v113
	v_add_f32_e32 v113, s100, v113
	v_add_f32_e32 v113, vcc_lo, v113
	v_fmamk_f32 v144, v113, 0x3b000000, v131
	v_rsq_f32_e32 v144, v144
	s_nop 0
	v_pk_mul_f32 v[104:105], v[96:97], v[144:145] op_sel_hi:[1,0]
	v_pk_mul_f32 v[104:105], v[104:105], v[120:121]
	v_cvt_pk_bf16_f32 v116, v104, v105
	v_pk_mul_f32 v[104:105], v[98:99], v[144:145] op_sel_hi:[1,0]
	v_pk_mul_f32 v[104:105], v[104:105], v[122:123]
	v_cvt_pk_bf16_f32 v117, v104, v105
	v_pk_mul_f32 v[104:105], v[100:101], v[144:145] op_sel_hi:[1,0]
	v_pk_mul_f32 v[104:105], v[104:105], v[124:125]
	v_cvt_pk_bf16_f32 v118, v104, v105
	v_pk_mul_f32 v[104:105], v[102:103], v[144:145] op_sel_hi:[1,0]
	v_pk_mul_f32 v[104:105], v[104:105], v[126:127]
	v_cvt_pk_bf16_f32 v119, v104, v105
	v_add_u32_e32 v138, 0x3800000, v135
	global_store_dwordx4 v138, v[116:119], s[34:35]
	s_waitcnt vmcnt(7)
	v_lshlrev_b32_e32 v104, 16, v84
	v_and_b32_e32 v105, 0xffff0000, v84
	v_lshlrev_b32_e32 v106, 16, v88
	v_and_b32_e32 v107, 0xffff0000, v88
	v_lshlrev_b32_e32 v108, 16, v92
	v_and_b32_e32 v109, 0xffff0000, v92
	v_pk_add_f32 v[104:105], v[104:105], v[106:107]
	v_pk_mul_f32 v[110:111], v[108:109], v[108:109]
	v_pk_fma_f32 v[110:111], v[110:111], v[140:141], 1.0 op_sel_hi:[1,0,0]
	v_pk_mul_f32 v[110:111], v[110:111], v[108:109]
	v_pk_mul_f32 v[110:111], v[110:111], v[142:143] op_sel_hi:[1,0]
	v_exp_f32_e32 v110, v110
	v_exp_f32_e32 v111, v111
	s_nop 0
	v_pk_add_f32 v[110:111], v[110:111], 1.0 op_sel_hi:[1,0]
	v_rcp_f32_e32 v110, v110
	v_rcp_f32_e32 v111, v111
	s_nop 0
	v_pk_mul_f32 v[110:111], v[110:111], v[108:109]
	v_pk_mul_f32 v[96:97], v[104:105], v[110:111]
	v_pk_mul_f32 v[112:113], v[96:97], v[96:97]
	v_lshlrev_b32_e32 v104, 16, v85
	v_and_b32_e32 v105, 0xffff0000, v85
	v_lshlrev_b32_e32 v106, 16, v89
	v_and_b32_e32 v107, 0xffff0000, v89
	v_lshlrev_b32_e32 v108, 16, v93
	v_and_b32_e32 v109, 0xffff0000, v93
	v_pk_add_f32 v[104:105], v[104:105], v[106:107]
	v_pk_mul_f32 v[110:111], v[108:109], v[108:109]
	v_pk_fma_f32 v[110:111], v[110:111], v[140:141], 1.0 op_sel_hi:[1,0,0]
	v_pk_mul_f32 v[110:111], v[110:111], v[108:109]
	v_pk_mul_f32 v[110:111], v[110:111], v[142:143] op_sel_hi:[1,0]
	v_exp_f32_e32 v110, v110
	v_exp_f32_e32 v111, v111
	s_nop 0
	v_pk_add_f32 v[110:111], v[110:111], 1.0 op_sel_hi:[1,0]
	v_rcp_f32_e32 v110, v110
	v_rcp_f32_e32 v111, v111
	s_nop 0
	v_pk_mul_f32 v[110:111], v[110:111], v[108:109]
	v_pk_mul_f32 v[98:99], v[104:105], v[110:111]
	v_pk_fma_f32 v[112:113], v[98:99], v[98:99], v[112:113]
	v_lshlrev_b32_e32 v104, 16, v86
	v_and_b32_e32 v105, 0xffff0000, v86
	v_lshlrev_b32_e32 v106, 16, v90
	v_and_b32_e32 v107, 0xffff0000, v90
	v_lshlrev_b32_e32 v108, 16, v94
	v_and_b32_e32 v109, 0xffff0000, v94
	v_pk_add_f32 v[104:105], v[104:105], v[106:107]
	v_pk_mul_f32 v[110:111], v[108:109], v[108:109]
	v_pk_fma_f32 v[110:111], v[110:111], v[140:141], 1.0 op_sel_hi:[1,0,0]
	v_pk_mul_f32 v[110:111], v[110:111], v[108:109]
	v_pk_mul_f32 v[110:111], v[110:111], v[142:143] op_sel_hi:[1,0]
	v_exp_f32_e32 v110, v110
	v_exp_f32_e32 v111, v111
	s_nop 0
	v_pk_add_f32 v[110:111], v[110:111], 1.0 op_sel_hi:[1,0]
	v_rcp_f32_e32 v110, v110
	v_rcp_f32_e32 v111, v111
	s_nop 0
	v_pk_mul_f32 v[110:111], v[110:111], v[108:109]
	v_pk_mul_f32 v[100:101], v[104:105], v[110:111]
	v_pk_fma_f32 v[112:113], v[100:101], v[100:101], v[112:113]
	v_lshlrev_b32_e32 v104, 16, v87
	v_and_b32_e32 v105, 0xffff0000, v87
	v_lshlrev_b32_e32 v106, 16, v91
	v_and_b32_e32 v107, 0xffff0000, v91
	v_lshlrev_b32_e32 v108, 16, v95
	v_and_b32_e32 v109, 0xffff0000, v95
	v_pk_add_f32 v[104:105], v[104:105], v[106:107]
	v_pk_mul_f32 v[110:111], v[108:109], v[108:109]
	v_pk_fma_f32 v[110:111], v[110:111], v[140:141], 1.0 op_sel_hi:[1,0,0]
	v_pk_mul_f32 v[110:111], v[110:111], v[108:109]
	v_pk_mul_f32 v[110:111], v[110:111], v[142:143] op_sel_hi:[1,0]
	v_exp_f32_e32 v110, v110
	v_exp_f32_e32 v111, v111
	s_nop 0
	v_pk_add_f32 v[110:111], v[110:111], 1.0 op_sel_hi:[1,0]
	v_rcp_f32_e32 v110, v110
	v_rcp_f32_e32 v111, v111
	s_nop 0
	v_pk_mul_f32 v[110:111], v[110:111], v[108:109]
	v_pk_mul_f32 v[102:103], v[104:105], v[110:111]
	v_pk_fma_f32 v[112:113], v[102:103], v[102:103], v[112:113]
	v_add_f32_e32 v112, v112, v113
	s_nop 1
	v_add_f32_dpp v112, v112, v112 quad_perm:[1,0,3,2] row_mask:0xf bank_mask:0xf
	s_nop 1
	v_add_f32_dpp v112, v112, v112 quad_perm:[2,3,0,1] row_mask:0xf bank_mask:0xf
	s_nop 1
	v_add_f32_dpp v112, v112, v112 row_half_mirror row_mask:0xf bank_mask:0xf
	s_nop 1
	v_add_f32_dpp v112, v112, v112 row_mirror row_mask:0xf bank_mask:0xf
	s_nop 1
	v_readlane_b32 s98, v112, 0
	v_readlane_b32 s99, v112, 16
	v_readlane_b32 s100, v112, 32
	v_readlane_b32 vcc_lo, v112, 48
	s_nop 1
	v_mov_b32_e32 v113, s98
	v_add_f32_e32 v113, s99, v113
	v_add_f32_e32 v113, s100, v113
	v_add_f32_e32 v113, vcc_lo, v113
	v_fmamk_f32 v144, v113, 0x3b000000, v131
	v_rsq_f32_e32 v144, v144
	s_nop 0
	v_pk_mul_f32 v[104:105], v[96:97], v[144:145] op_sel_hi:[1,0]
	v_pk_mul_f32 v[104:105], v[104:105], v[120:121]
	v_cvt_pk_bf16_f32 v116, v104, v105
	v_pk_mul_f32 v[104:105], v[98:99], v[144:145] op_sel_hi:[1,0]
	v_pk_mul_f32 v[104:105], v[104:105], v[122:123]
	v_cvt_pk_bf16_f32 v117, v104, v105
	v_pk_mul_f32 v[104:105], v[100:101], v[144:145] op_sel_hi:[1,0]
	v_pk_mul_f32 v[104:105], v[104:105], v[124:125]
	v_cvt_pk_bf16_f32 v118, v104, v105
	v_pk_mul_f32 v[104:105], v[102:103], v[144:145] op_sel_hi:[1,0]
	v_pk_mul_f32 v[104:105], v[104:105], v[126:127]
	v_cvt_pk_bf16_f32 v119, v104, v105
	v_add_u32_e32 v138, 0x3c00000, v135
	global_store_dwordx4 v138, v[116:119], s[34:35]
	s_cmp_eq_u32 s101, 0
	s_cbranch_scc1 .Lcomb_retA
	s_branch .Lcomb_retB

.LBB0_601:
	s_cmp_eq_u32 s63, 6
	s_cbranch_scc1 .Lp5_scale

.Lp5_scale:
	v_fmamk_f32 v244, v169, 0x3b000000, v152
	v_rsq_f32_e32 v244, v244
	s_nop 0
	v_mul_f32_e32 v112, v244, v112
	v_mul_f32_e32 v113, v244, v113
	v_mul_f32_e32 v114, v244, v114
	v_mul_f32_e32 v115, v244, v115
	v_mul_f32_e32 v116, v244, v116
	v_mul_f32_e32 v117, v244, v117
	v_mul_f32_e32 v118, v244, v118
	v_mul_f32_e32 v119, v244, v119
	v_mul_f32_e32 v120, v244, v120
	v_mul_f32_e32 v121, v244, v121
	v_mul_f32_e32 v122, v244, v122
	v_mul_f32_e32 v123, v244, v123
	v_mul_f32_e32 v124, v244, v124
	v_mul_f32_e32 v125, v244, v125
	v_mul_f32_e32 v126, v244, v126
	v_mul_f32_e32 v127, v244, v127
	v_fmamk_f32 v244, v168, 0x3b000000, v152
	v_rsq_f32_e32 v244, v244
	s_nop 0
	v_mul_f32_e32 v96, v244, v96
	v_mul_f32_e32 v97, v244, v97
	v_mul_f32_e32 v98, v244, v98
	v_mul_f32_e32 v99, v244, v99
	v_mul_f32_e32 v100, v244, v100
	v_mul_f32_e32 v101, v244, v101
	v_mul_f32_e32 v102, v244, v102
	v_mul_f32_e32 v103, v244, v103
	v_mul_f32_e32 v104, v244, v104
	v_mul_f32_e32 v105, v244, v105
	v_mul_f32_e32 v106, v244, v106
	v_mul_f32_e32 v107, v244, v107
	v_mul_f32_e32 v108, v244, v108
	v_mul_f32_e32 v109, v244, v109
	v_mul_f32_e32 v110, v244, v110
	v_mul_f32_e32 v111, v244, v111
	v_fmamk_f32 v244, v167, 0x3b000000, v152
	v_rsq_f32_e32 v244, v244
	s_nop 0
	v_mul_f32_e32 v80, v244, v80
	v_mul_f32_e32 v81, v244, v81
	v_mul_f32_e32 v82, v244, v82
	v_mul_f32_e32 v83, v244, v83
	v_mul_f32_e32 v84, v244, v84
	v_mul_f32_e32 v85, v244, v85
	v_mul_f32_e32 v86, v244, v86
	v_mul_f32_e32 v87, v244, v87
	v_mul_f32_e32 v88, v244, v88
	v_mul_f32_e32 v89, v244, v89
	v_mul_f32_e32 v90, v244, v90
	v_mul_f32_e32 v91, v244, v91
	v_mul_f32_e32 v92, v244, v92
	v_mul_f32_e32 v93, v244, v93
	v_mul_f32_e32 v94, v244, v94
	v_mul_f32_e32 v95, v244, v95
	v_fmamk_f32 v244, v166, 0x3b000000, v152
	v_rsq_f32_e32 v244, v244
	s_nop 0
	v_mul_f32_e32 v64, v244, v64
	v_mul_f32_e32 v65, v244, v65
	v_mul_f32_e32 v66, v244, v66
	v_mul_f32_e32 v67, v244, v67
	v_mul_f32_e32 v68, v244, v68
	v_mul_f32_e32 v69, v244, v69
	v_mul_f32_e32 v70, v244, v70
	v_mul_f32_e32 v71, v244, v71
	v_mul_f32_e32 v72, v244, v72
	v_mul_f32_e32 v73, v244, v73
	v_mul_f32_e32 v74, v244, v74
	v_mul_f32_e32 v75, v244, v75
	v_mul_f32_e32 v76, v244, v76
	v_mul_f32_e32 v77, v244, v77
	v_mul_f32_e32 v78, v244, v78
	v_mul_f32_e32 v79, v244, v79
	v_fmamk_f32 v244, v165, 0x3b000000, v152
	v_rsq_f32_e32 v244, v244
	s_nop 0
	v_mul_f32_e32 v48, v244, v48
	v_mul_f32_e32 v49, v244, v49
	v_mul_f32_e32 v50, v244, v50
	v_mul_f32_e32 v51, v244, v51
	v_mul_f32_e32 v52, v244, v52
	v_mul_f32_e32 v53, v244, v53
	v_mul_f32_e32 v54, v244, v54
	v_mul_f32_e32 v55, v244, v55
	v_mul_f32_e32 v56, v244, v56
	v_mul_f32_e32 v57, v244, v57
	v_mul_f32_e32 v58, v244, v58
	v_mul_f32_e32 v59, v244, v59
	v_mul_f32_e32 v60, v244, v60
	v_mul_f32_e32 v61, v244, v61
	v_mul_f32_e32 v62, v244, v62
	v_mul_f32_e32 v63, v244, v63
	v_fmamk_f32 v244, v164, 0x3b000000, v152
	v_rsq_f32_e32 v244, v244
	s_nop 0
	v_mul_f32_e32 v32, v244, v32
	v_mul_f32_e32 v33, v244, v33
	v_mul_f32_e32 v34, v244, v34
	v_mul_f32_e32 v35, v244, v35
	v_mul_f32_e32 v36, v244, v36
	v_mul_f32_e32 v37, v244, v37
	v_mul_f32_e32 v38, v244, v38
	v_mul_f32_e32 v39, v244, v39
	v_mul_f32_e32 v40, v244, v40
	v_mul_f32_e32 v41, v244, v41
	v_mul_f32_e32 v42, v244, v42
	v_mul_f32_e32 v43, v244, v43
	v_mul_f32_e32 v44, v244, v44
	v_mul_f32_e32 v45, v244, v45
	v_mul_f32_e32 v46, v244, v46
	v_mul_f32_e32 v47, v244, v47
	v_fmamk_f32 v244, v155, 0x3b000000, v152
	v_rsq_f32_e32 v244, v244
	s_nop 0
	v_mul_f32_e32 v16, v244, v16
	v_mul_f32_e32 v17, v244, v17
	v_mul_f32_e32 v18, v244, v18
	v_mul_f32_e32 v19, v244, v19
	v_mul_f32_e32 v20, v244, v20
	v_mul_f32_e32 v21, v244, v21
	v_mul_f32_e32 v22, v244, v22
	v_mul_f32_e32 v23, v244, v23
	v_mul_f32_e32 v24, v244, v24
	v_mul_f32_e32 v25, v244, v25
	v_mul_f32_e32 v26, v244, v26
	v_mul_f32_e32 v27, v244, v27
	v_mul_f32_e32 v28, v244, v28
	v_mul_f32_e32 v29, v244, v29
	v_mul_f32_e32 v30, v244, v30
	v_mul_f32_e32 v31, v244, v31
	v_fmamk_f32 v244, v154, 0x3b000000, v152
	v_rsq_f32_e32 v244, v244
	s_nop 0
	v_mul_f32_e32 v0, v244, v0
	v_mul_f32_e32 v1, v244, v1
	v_mul_f32_e32 v2, v244, v2
	v_mul_f32_e32 v3, v244, v3
	v_mul_f32_e32 v4, v244, v4
	v_mul_f32_e32 v5, v244, v5
	v_mul_f32_e32 v6, v244, v6
	v_mul_f32_e32 v7, v244, v7
	v_mul_f32_e32 v8, v244, v8
	v_mul_f32_e32 v9, v244, v9
	v_mul_f32_e32 v10, v244, v10
	v_mul_f32_e32 v11, v244, v11
	v_mul_f32_e32 v12, v244, v12
	v_mul_f32_e32 v13, v244, v13
	v_mul_f32_e32 v14, v244, v14
	v_mul_f32_e32 v15, v244, v15
	s_branch .Lp5_scale_ret

.LBB0_605:
	v_lshl_add_u32 v146, s44, 8, v148
	v_lshl_or_b32 v144, s42, 8, v150
	v_ashrrev_i32_e32 v147, 31, v146
	v_ashrrev_i32_e32 v145, 31, v144
	v_lshlrev_b64 v[170:171], 10, v[146:147]
	v_lshl_add_u64 v[178:179], v[170:171], 0, v[144:145]
	v_lshl_add_u64 v[180:181], v[178:179], 2, s[36:37]
	global_load_dwordx4 v[170:173], v[180:181], off nt
	global_load_dwordx4 v[174:177], v[180:181], off offset:16 nt
	v_fmamk_f32 v169, v169, 0x3b000000, v152
	v_rsq_f32_e32 v182, v169
	v_lshl_add_u64 v[178:179], v[178:179], 1, s[4:5]
	s_waitcnt vmcnt(0)
	v_pk_add_f32 v[126:127], v[126:127], v[172:173]
	v_pk_add_f32 v[184:185], v[124:125], v[170:171]
	v_pk_add_f32 v[176:177], v[122:123], v[176:177]
	v_pk_add_f32 v[174:175], v[120:121], v[174:175]
	v_cvt_pk_bf16_f32 v120, v184, v185
	v_cvt_pk_bf16_f32 v121, v126, v127
	v_cvt_pk_bf16_f32 v122, v174, v175
	v_cvt_pk_bf16_f32 v123, v176, v177
	global_store_dwordx4 v[178:179], v[120:123], off
	global_load_dwordx4 v[122:125], v[180:181], off offset:512 nt
	s_nop 0
	global_load_dwordx4 v[170:173], v[180:181], off offset:528 nt
	v_mul_f32_e32 v169, v185, v185
	v_mul_f32_e32 v127, v127, v127
	v_and_b32_e32 v121, 64, v153
	v_mul_f32_e32 v175, v175, v175
	v_fmac_f32_e32 v169, v184, v184
	v_fmac_f32_e32 v127, v126, v126
	v_xor_b32_e32 v120, 16, v153
	v_add_u32_e32 v121, 64, v121
	v_mul_f32_e32 v177, v177, v177
	v_fmac_f32_e32 v175, v174, v174
	v_add_f32_e32 v126, v169, v127
	v_cmp_lt_i32_e32 vcc, v120, v121
	v_fmac_f32_e32 v177, v176, v176
	v_add_f32_e32 v126, v126, v175
	v_cndmask_b32_e32 v120, v153, v120, vcc
	v_add_f32_e32 v126, v177, v126
	v_lshlrev_b32_e32 v120, 2, v120
	s_waitcnt vmcnt(1)
	v_pk_add_f32 v[118:119], v[118:119], v[124:125]
	v_pk_add_f32 v[116:117], v[116:117], v[122:123]
	s_waitcnt vmcnt(0)
	v_pk_add_f32 v[124:125], v[112:113], v[170:171]
	v_mul_f32_e32 v112, v117, v117
	v_mul_f32_e32 v113, v119, v119
	v_pk_add_f32 v[122:123], v[114:115], v[172:173]
	v_mul_f32_e32 v114, v125, v125
	v_fmac_f32_e32 v112, v116, v116
	v_fmac_f32_e32 v113, v118, v118
	v_mul_f32_e32 v115, v123, v123
	v_fmac_f32_e32 v114, v124, v124
	v_add_f32_e32 v112, v112, v113
	v_fmac_f32_e32 v115, v122, v122
	v_add_f32_e32 v112, v112, v114
	v_add_f32_e32 v112, v115, v112
	v_add_f32_e32 v112, v126, v112
	ds_bpermute_b32 v113, v120, v112
	v_xor_b32_e32 v114, 32, v153
	v_cmp_lt_i32_e32 vcc, v114, v121
	v_cvt_pk_bf16_f32 v116, v116, v117
	v_cvt_pk_bf16_f32 v117, v118, v119
	s_waitcnt lgkmcnt(0)
	v_add_f32_e32 v112, v112, v113
	v_cvt_pk_bf16_f32 v118, v124, v125
	v_cvt_pk_bf16_f32 v119, v122, v123
	v_cndmask_b32_e32 v114, v153, v114, vcc
	v_lshlrev_b32_e32 v114, 2, v114
	ds_bpermute_b32 v113, v114, v112
	global_store_dwordx4 v[178:179], v[116:119], off offset:256
	s_and_saveexec_b64 s[42:43], s[0:1]
	s_cbranch_execz .LBB0_607
	v_lshl_add_u64 v[116:117], v[146:147], 2, s[8:9]
	s_waitcnt lgkmcnt(0)
	v_add_f32_e32 v112, v112, v113
	global_atomic_add_f32 v[116:117], v112, off
.LBB0_607:
	s_or_b64 exec, exec, s[42:43]
	v_or_b32_e32 v112, 16, v146
	s_waitcnt lgkmcnt(0)
	v_ashrrev_i32_e32 v113, 31, v112
	v_lshlrev_b64 v[116:117], 10, v[112:113]
	v_lshl_add_u64 v[126:127], v[116:117], 0, v[144:145]
	v_lshl_add_u64 v[170:171], v[126:127], 2, s[36:37]
	global_load_dwordx4 v[116:119], v[170:171], off nt
	global_load_dwordx4 v[122:125], v[170:171], off offset:16 nt
	v_fmamk_f32 v115, v168, 0x3b000000, v152
	v_rsq_f32_e32 v168, v115
	v_lshl_add_u64 v[126:127], v[126:127], 1, s[4:5]
	s_waitcnt vmcnt(1)
	v_pk_add_f32 v[118:119], v[110:111], v[118:119]
	v_pk_add_f32 v[116:117], v[108:109], v[116:117]
	s_waitcnt vmcnt(0)
	v_pk_add_f32 v[124:125], v[106:107], v[124:125]
	v_pk_add_f32 v[122:123], v[104:105], v[122:123]
	v_cvt_pk_bf16_f32 v104, v116, v117
	v_cvt_pk_bf16_f32 v105, v118, v119
	v_cvt_pk_bf16_f32 v106, v122, v123
	v_cvt_pk_bf16_f32 v107, v124, v125
	global_store_dwordx4 v[126:127], v[104:107], off
	global_load_dwordx4 v[104:107], v[170:171], off offset:512 nt
	s_nop 0
	global_load_dwordx4 v[108:111], v[170:171], off offset:528 nt
	v_mul_f32_e32 v115, v117, v117
	v_mul_f32_e32 v117, v119, v119
	v_mul_f32_e32 v119, v123, v123
	v_fmac_f32_e32 v115, v116, v116
	v_fmac_f32_e32 v117, v118, v118
	v_mul_f32_e32 v121, v125, v125
	v_fmac_f32_e32 v119, v122, v122
	v_add_f32_e32 v115, v115, v117
	v_fmac_f32_e32 v121, v124, v124
	v_add_f32_e32 v115, v115, v119
	v_add_f32_e32 v115, v121, v115
	s_waitcnt vmcnt(1)
	v_pk_add_f32 v[102:103], v[102:103], v[106:107]
	v_pk_add_f32 v[100:101], v[100:101], v[104:105]
	s_waitcnt vmcnt(0)
	v_pk_add_f32 v[106:107], v[96:97], v[108:109]
	v_mul_f32_e32 v96, v101, v101
	v_mul_f32_e32 v97, v103, v103
	v_pk_add_f32 v[104:105], v[98:99], v[110:111]
	v_mul_f32_e32 v98, v107, v107
	v_fmac_f32_e32 v96, v100, v100
	v_fmac_f32_e32 v97, v102, v102
	v_mul_f32_e32 v99, v105, v105
	v_fmac_f32_e32 v98, v106, v106
	v_add_f32_e32 v96, v96, v97
	v_add_f32_e32 v96, v96, v98
	v_fmac_f32_e32 v99, v104, v104
	v_add_f32_e32 v96, v99, v96
	v_add_f32_e32 v96, v115, v96
	ds_bpermute_b32 v97, v120, v96
	v_cvt_pk_bf16_f32 v98, v100, v101
	v_cvt_pk_bf16_f32 v99, v102, v103
	v_cvt_pk_bf16_f32 v100, v106, v107
	v_cvt_pk_bf16_f32 v101, v104, v105
	s_waitcnt lgkmcnt(0)
	v_add_f32_e32 v96, v96, v97
	ds_bpermute_b32 v97, v114, v96
	global_store_dwordx4 v[126:127], v[98:101], off offset:256
	s_and_saveexec_b64 s[42:43], s[0:1]
	s_cbranch_execz .LBB0_609
	v_lshl_add_u64 v[98:99], v[112:113], 2, s[8:9]
	s_waitcnt lgkmcnt(0)
	v_add_f32_e32 v96, v96, v97
	global_atomic_add_f32 v[98:99], v96, off
.LBB0_609:
	s_or_b64 exec, exec, s[42:43]
	v_or_b32_e32 v96, 32, v146
	s_waitcnt lgkmcnt(0)
	v_ashrrev_i32_e32 v97, 31, v96
	v_lshlrev_b64 v[98:99], 10, v[96:97]
	v_lshl_add_u64 v[106:107], v[98:99], 0, v[144:145]
	v_lshl_add_u64 v[108:109], v[106:107], 2, s[36:37]
	global_load_dwordx4 v[98:101], v[108:109], off nt
	global_load_dwordx4 v[102:105], v[108:109], off offset:16 nt
	v_fmamk_f32 v110, v167, 0x3b000000, v152
	v_rsq_f32_e32 v110, v110
	v_lshl_add_u64 v[106:107], v[106:107], 1, s[4:5]
	s_waitcnt vmcnt(1)
	v_pk_add_f32 v[100:101], v[94:95], v[100:101]
	v_pk_add_f32 v[98:99], v[92:93], v[98:99]
	s_waitcnt vmcnt(0)
	v_pk_add_f32 v[104:105], v[90:91], v[104:105]
	v_pk_add_f32 v[102:103], v[88:89], v[102:103]
	v_cvt_pk_bf16_f32 v88, v98, v99
	v_cvt_pk_bf16_f32 v89, v100, v101
	v_cvt_pk_bf16_f32 v90, v102, v103
	v_cvt_pk_bf16_f32 v91, v104, v105
	global_store_dwordx4 v[106:107], v[88:91], off
	global_load_dwordx4 v[88:91], v[108:109], off offset:512 nt
	s_nop 0
	global_load_dwordx4 v[92:95], v[108:109], off offset:528 nt
	v_mul_f32_e32 v99, v99, v99
	v_mul_f32_e32 v101, v101, v101
	v_mul_f32_e32 v103, v103, v103
	v_fmac_f32_e32 v99, v98, v98
	v_fmac_f32_e32 v101, v100, v100
	v_mul_f32_e32 v105, v105, v105
	v_fmac_f32_e32 v103, v102, v102
	v_add_f32_e32 v98, v99, v101
	v_fmac_f32_e32 v105, v104, v104
	v_add_f32_e32 v98, v98, v103
	v_add_f32_e32 v98, v105, v98
	s_waitcnt vmcnt(1)
	v_pk_add_f32 v[86:87], v[86:87], v[90:91]
	v_pk_add_f32 v[84:85], v[84:85], v[88:89]
	s_waitcnt vmcnt(0)
	v_pk_add_f32 v[90:91], v[80:81], v[92:93]
	v_mul_f32_e32 v80, v85, v85
	v_mul_f32_e32 v81, v87, v87
	v_pk_add_f32 v[88:89], v[82:83], v[94:95]
	v_mul_f32_e32 v82, v91, v91
	v_fmac_f32_e32 v80, v84, v84
	v_fmac_f32_e32 v81, v86, v86
	v_mul_f32_e32 v83, v89, v89
	v_fmac_f32_e32 v82, v90, v90
	v_add_f32_e32 v80, v80, v81
	v_add_f32_e32 v80, v80, v82
	v_fmac_f32_e32 v83, v88, v88
	v_add_f32_e32 v80, v83, v80
	v_add_f32_e32 v80, v98, v80
	ds_bpermute_b32 v81, v120, v80
	v_cvt_pk_bf16_f32 v82, v84, v85
	v_cvt_pk_bf16_f32 v83, v86, v87
	v_cvt_pk_bf16_f32 v84, v90, v91
	v_cvt_pk_bf16_f32 v85, v88, v89
	s_waitcnt lgkmcnt(0)
	v_add_f32_e32 v80, v80, v81
	ds_bpermute_b32 v81, v114, v80
	global_store_dwordx4 v[106:107], v[82:85], off offset:256
	s_and_saveexec_b64 s[42:43], s[0:1]
	s_cbranch_execz .LBB0_611
	v_lshl_add_u64 v[82:83], v[96:97], 2, s[8:9]
	s_waitcnt lgkmcnt(0)
	v_add_f32_e32 v80, v80, v81
	global_atomic_add_f32 v[82:83], v80, off
.LBB0_611:
	s_or_b64 exec, exec, s[42:43]
	v_or_b32_e32 v80, 48, v146
	s_waitcnt lgkmcnt(0)
	v_ashrrev_i32_e32 v81, 31, v80
	v_lshlrev_b64 v[82:83], 10, v[80:81]
	v_lshl_add_u64 v[90:91], v[82:83], 0, v[144:145]
	v_lshl_add_u64 v[92:93], v[90:91], 2, s[36:37]
	global_load_dwordx4 v[82:85], v[92:93], off nt
	global_load_dwordx4 v[86:89], v[92:93], off offset:16 nt
	v_fmamk_f32 v94, v166, 0x3b000000, v152
	v_rsq_f32_e32 v94, v94
	v_lshl_add_u64 v[90:91], v[90:91], 1, s[4:5]
	s_waitcnt vmcnt(1)
	v_pk_add_f32 v[84:85], v[78:79], v[84:85]
	v_pk_add_f32 v[82:83], v[76:77], v[82:83]
	s_waitcnt vmcnt(0)
	v_pk_add_f32 v[88:89], v[74:75], v[88:89]
	v_pk_add_f32 v[86:87], v[72:73], v[86:87]
	v_cvt_pk_bf16_f32 v72, v82, v83
	v_cvt_pk_bf16_f32 v73, v84, v85
	v_cvt_pk_bf16_f32 v74, v86, v87
	v_cvt_pk_bf16_f32 v75, v88, v89
	global_store_dwordx4 v[90:91], v[72:75], off
	global_load_dwordx4 v[72:75], v[92:93], off offset:512 nt
	s_nop 0
	global_load_dwordx4 v[76:79], v[92:93], off offset:528 nt
	v_mul_f32_e32 v83, v83, v83
	v_mul_f32_e32 v85, v85, v85
	v_mul_f32_e32 v87, v87, v87
	v_fmac_f32_e32 v83, v82, v82
	v_fmac_f32_e32 v85, v84, v84
	v_mul_f32_e32 v89, v89, v89
	v_fmac_f32_e32 v87, v86, v86
	v_add_f32_e32 v82, v83, v85
	v_fmac_f32_e32 v89, v88, v88
	v_add_f32_e32 v82, v82, v87
	v_add_f32_e32 v82, v89, v82
	s_waitcnt vmcnt(1)
	v_pk_add_f32 v[70:71], v[70:71], v[74:75]
	v_pk_add_f32 v[68:69], v[68:69], v[72:73]
	s_waitcnt vmcnt(0)
	v_pk_add_f32 v[74:75], v[64:65], v[76:77]
	v_mul_f32_e32 v64, v69, v69
	v_mul_f32_e32 v65, v71, v71
	v_pk_add_f32 v[72:73], v[66:67], v[78:79]
	v_mul_f32_e32 v66, v75, v75
	v_fmac_f32_e32 v64, v68, v68
	v_fmac_f32_e32 v65, v70, v70
	v_mul_f32_e32 v67, v73, v73
	v_fmac_f32_e32 v66, v74, v74
	v_add_f32_e32 v64, v64, v65
	v_add_f32_e32 v64, v64, v66
	v_fmac_f32_e32 v67, v72, v72
	v_add_f32_e32 v64, v67, v64
	v_add_f32_e32 v64, v82, v64
	ds_bpermute_b32 v65, v120, v64
	v_cvt_pk_bf16_f32 v66, v68, v69
	v_cvt_pk_bf16_f32 v67, v70, v71
	v_cvt_pk_bf16_f32 v68, v74, v75
	v_cvt_pk_bf16_f32 v69, v72, v73
	s_waitcnt lgkmcnt(0)
	v_add_f32_e32 v64, v64, v65
	ds_bpermute_b32 v65, v114, v64
	global_store_dwordx4 v[90:91], v[66:69], off offset:256
	s_and_saveexec_b64 s[42:43], s[0:1]
	s_cbranch_execz .LBB0_613
	v_lshl_add_u64 v[66:67], v[80:81], 2, s[8:9]
	s_waitcnt lgkmcnt(0)
	v_add_f32_e32 v64, v64, v65
	global_atomic_add_f32 v[66:67], v64, off
.LBB0_613:
	s_or_b64 exec, exec, s[42:43]
	v_add_u32_e32 v64, 0x80, v146
	s_waitcnt lgkmcnt(0)
	v_ashrrev_i32_e32 v65, 31, v64
	v_lshlrev_b64 v[66:67], 10, v[64:65]
	v_lshl_add_u64 v[74:75], v[66:67], 0, v[144:145]
	v_lshl_add_u64 v[76:77], v[74:75], 2, s[36:37]
	global_load_dwordx4 v[66:69], v[76:77], off nt
	global_load_dwordx4 v[70:73], v[76:77], off offset:16 nt
	v_fmamk_f32 v78, v165, 0x3b000000, v152
	v_rsq_f32_e32 v78, v78
	v_lshl_add_u64 v[74:75], v[74:75], 1, s[4:5]
	s_waitcnt vmcnt(1)
	v_pk_add_f32 v[68:69], v[62:63], v[68:69]
	v_pk_add_f32 v[66:67], v[60:61], v[66:67]
	s_waitcnt vmcnt(0)
	v_pk_add_f32 v[72:73], v[58:59], v[72:73]
	v_pk_add_f32 v[70:71], v[56:57], v[70:71]
	v_cvt_pk_bf16_f32 v56, v66, v67
	v_cvt_pk_bf16_f32 v57, v68, v69
	v_cvt_pk_bf16_f32 v58, v70, v71
	v_cvt_pk_bf16_f32 v59, v72, v73
	global_store_dwordx4 v[74:75], v[56:59], off
	global_load_dwordx4 v[56:59], v[76:77], off offset:512 nt
	s_nop 0
	global_load_dwordx4 v[60:63], v[76:77], off offset:528 nt
	v_mul_f32_e32 v67, v67, v67
	v_mul_f32_e32 v69, v69, v69
	v_mul_f32_e32 v71, v71, v71
	v_fmac_f32_e32 v67, v66, v66
	v_fmac_f32_e32 v69, v68, v68
	v_mul_f32_e32 v73, v73, v73
	v_fmac_f32_e32 v71, v70, v70
	v_add_f32_e32 v66, v67, v69
	v_fmac_f32_e32 v73, v72, v72
	v_add_f32_e32 v66, v66, v71
	v_add_f32_e32 v66, v73, v66
	s_waitcnt vmcnt(1)
	v_pk_add_f32 v[54:55], v[54:55], v[58:59]
	v_pk_add_f32 v[52:53], v[52:53], v[56:57]
	s_waitcnt vmcnt(0)
	v_pk_add_f32 v[58:59], v[48:49], v[60:61]
	v_mul_f32_e32 v48, v53, v53
	v_mul_f32_e32 v49, v55, v55
	v_pk_add_f32 v[56:57], v[50:51], v[62:63]
	v_mul_f32_e32 v50, v59, v59
	v_fmac_f32_e32 v48, v52, v52
	v_fmac_f32_e32 v49, v54, v54
	v_mul_f32_e32 v51, v57, v57
	v_fmac_f32_e32 v50, v58, v58
	v_add_f32_e32 v48, v48, v49
	v_add_f32_e32 v48, v48, v50
	v_fmac_f32_e32 v51, v56, v56
	v_add_f32_e32 v48, v51, v48
	v_add_f32_e32 v48, v66, v48
	ds_bpermute_b32 v49, v120, v48
	v_cvt_pk_bf16_f32 v50, v52, v53
	v_cvt_pk_bf16_f32 v51, v54, v55
	v_cvt_pk_bf16_f32 v52, v58, v59
	v_cvt_pk_bf16_f32 v53, v56, v57
	s_waitcnt lgkmcnt(0)
	v_add_f32_e32 v48, v48, v49
	ds_bpermute_b32 v49, v114, v48
	global_store_dwordx4 v[74:75], v[50:53], off offset:256
	s_and_saveexec_b64 s[42:43], s[0:1]
	s_cbranch_execz .LBB0_615
	v_lshl_add_u64 v[50:51], v[64:65], 2, s[8:9]
	s_waitcnt lgkmcnt(0)
	v_add_f32_e32 v48, v48, v49
	global_atomic_add_f32 v[50:51], v48, off
.LBB0_615:
	s_or_b64 exec, exec, s[42:43]
	v_add_u32_e32 v48, 0x90, v146
	s_waitcnt lgkmcnt(0)
	v_ashrrev_i32_e32 v49, 31, v48
	v_lshlrev_b64 v[50:51], 10, v[48:49]
	v_lshl_add_u64 v[58:59], v[50:51], 0, v[144:145]
	v_lshl_add_u64 v[60:61], v[58:59], 2, s[36:37]
	global_load_dwordx4 v[50:53], v[60:61], off nt
	global_load_dwordx4 v[54:57], v[60:61], off offset:16 nt
	v_fmamk_f32 v62, v164, 0x3b000000, v152
	v_rsq_f32_e32 v62, v62
	v_lshl_add_u64 v[58:59], v[58:59], 1, s[4:5]
	s_waitcnt vmcnt(1)
	v_pk_add_f32 v[52:53], v[46:47], v[52:53]
	v_pk_add_f32 v[50:51], v[44:45], v[50:51]
	s_waitcnt vmcnt(0)
	v_pk_add_f32 v[56:57], v[42:43], v[56:57]
	v_pk_add_f32 v[54:55], v[40:41], v[54:55]
	v_cvt_pk_bf16_f32 v40, v50, v51
	v_cvt_pk_bf16_f32 v41, v52, v53
	v_cvt_pk_bf16_f32 v42, v54, v55
	v_cvt_pk_bf16_f32 v43, v56, v57
	global_store_dwordx4 v[58:59], v[40:43], off
	global_load_dwordx4 v[40:43], v[60:61], off offset:512 nt
	s_nop 0
	global_load_dwordx4 v[44:47], v[60:61], off offset:528 nt
	v_mul_f32_e32 v51, v51, v51
	v_mul_f32_e32 v53, v53, v53
	v_mul_f32_e32 v55, v55, v55
	v_fmac_f32_e32 v51, v50, v50
	v_fmac_f32_e32 v53, v52, v52
	v_mul_f32_e32 v57, v57, v57
	v_fmac_f32_e32 v55, v54, v54
	v_add_f32_e32 v50, v51, v53
	v_fmac_f32_e32 v57, v56, v56
	v_add_f32_e32 v50, v50, v55
	v_add_f32_e32 v50, v57, v50
	s_waitcnt vmcnt(1)
	v_pk_add_f32 v[38:39], v[38:39], v[42:43]
	v_pk_add_f32 v[36:37], v[36:37], v[40:41]
	s_waitcnt vmcnt(0)
	v_pk_add_f32 v[42:43], v[32:33], v[44:45]
	v_mul_f32_e32 v32, v37, v37
	v_mul_f32_e32 v33, v39, v39
	v_pk_add_f32 v[40:41], v[34:35], v[46:47]
	v_mul_f32_e32 v34, v43, v43
	v_fmac_f32_e32 v32, v36, v36
	v_fmac_f32_e32 v33, v38, v38
	v_mul_f32_e32 v35, v41, v41
	v_fmac_f32_e32 v34, v42, v42
	v_add_f32_e32 v32, v32, v33
	v_add_f32_e32 v32, v32, v34
	v_fmac_f32_e32 v35, v40, v40
	v_add_f32_e32 v32, v35, v32
	v_add_f32_e32 v32, v50, v32
	ds_bpermute_b32 v33, v120, v32
	v_cvt_pk_bf16_f32 v34, v36, v37
	v_cvt_pk_bf16_f32 v35, v38, v39
	v_cvt_pk_bf16_f32 v36, v42, v43
	v_cvt_pk_bf16_f32 v37, v40, v41
	s_waitcnt lgkmcnt(0)
	v_add_f32_e32 v32, v32, v33
	ds_bpermute_b32 v33, v114, v32
	global_store_dwordx4 v[58:59], v[34:37], off offset:256
	s_and_saveexec_b64 s[42:43], s[0:1]
	s_cbranch_execz .LBB0_617
	v_lshl_add_u64 v[34:35], v[48:49], 2, s[8:9]
	s_waitcnt lgkmcnt(0)
	v_add_f32_e32 v32, v32, v33
	global_atomic_add_f32 v[34:35], v32, off
.LBB0_617:
	s_or_b64 exec, exec, s[42:43]
	v_add_u32_e32 v32, 0xa0, v146
	s_waitcnt lgkmcnt(0)
	v_ashrrev_i32_e32 v33, 31, v32
	v_lshlrev_b64 v[34:35], 10, v[32:33]
	v_lshl_add_u64 v[42:43], v[34:35], 0, v[144:145]
	v_lshl_add_u64 v[44:45], v[42:43], 2, s[36:37]
	global_load_dwordx4 v[34:37], v[44:45], off nt
	global_load_dwordx4 v[38:41], v[44:45], off offset:16 nt
	v_fmamk_f32 v46, v155, 0x3b000000, v152
	v_rsq_f32_e32 v46, v46
	v_lshl_add_u64 v[42:43], v[42:43], 1, s[4:5]
	s_waitcnt vmcnt(1)
	v_pk_add_f32 v[36:37], v[30:31], v[36:37]
	v_pk_add_f32 v[34:35], v[28:29], v[34:35]
	s_waitcnt vmcnt(0)
	v_pk_add_f32 v[40:41], v[26:27], v[40:41]
	v_pk_add_f32 v[38:39], v[24:25], v[38:39]
	v_cvt_pk_bf16_f32 v24, v34, v35
	v_cvt_pk_bf16_f32 v25, v36, v37
	v_cvt_pk_bf16_f32 v26, v38, v39
	v_cvt_pk_bf16_f32 v27, v40, v41
	global_store_dwordx4 v[42:43], v[24:27], off
	global_load_dwordx4 v[24:27], v[44:45], off offset:512 nt
	s_nop 0
	global_load_dwordx4 v[28:31], v[44:45], off offset:528 nt
	v_mul_f32_e32 v35, v35, v35
	v_mul_f32_e32 v37, v37, v37
	v_mul_f32_e32 v39, v39, v39
	v_fmac_f32_e32 v35, v34, v34
	v_fmac_f32_e32 v37, v36, v36
	v_mul_f32_e32 v41, v41, v41
	v_fmac_f32_e32 v39, v38, v38
	v_add_f32_e32 v34, v35, v37
	v_fmac_f32_e32 v41, v40, v40
	v_add_f32_e32 v34, v34, v39
	v_add_f32_e32 v34, v41, v34
	s_waitcnt vmcnt(1)
	v_pk_add_f32 v[22:23], v[22:23], v[26:27]
	v_pk_add_f32 v[20:21], v[20:21], v[24:25]
	s_waitcnt vmcnt(0)
	v_pk_add_f32 v[26:27], v[16:17], v[28:29]
	v_mul_f32_e32 v16, v21, v21
	v_mul_f32_e32 v17, v23, v23
	v_pk_add_f32 v[24:25], v[18:19], v[30:31]
	v_mul_f32_e32 v18, v27, v27
	v_fmac_f32_e32 v16, v20, v20
	v_fmac_f32_e32 v17, v22, v22
	v_mul_f32_e32 v19, v25, v25
	v_fmac_f32_e32 v18, v26, v26
	v_add_f32_e32 v16, v16, v17
	v_add_f32_e32 v16, v16, v18
	v_fmac_f32_e32 v19, v24, v24
	v_add_f32_e32 v16, v19, v16
	v_add_f32_e32 v16, v34, v16
	ds_bpermute_b32 v17, v120, v16
	v_cvt_pk_bf16_f32 v18, v20, v21
	v_cvt_pk_bf16_f32 v19, v22, v23
	v_cvt_pk_bf16_f32 v20, v26, v27
	v_cvt_pk_bf16_f32 v21, v24, v25
	s_waitcnt lgkmcnt(0)
	v_add_f32_e32 v16, v16, v17
	ds_bpermute_b32 v17, v114, v16
	global_store_dwordx4 v[42:43], v[18:21], off offset:256
	s_and_saveexec_b64 s[42:43], s[0:1]
	s_cbranch_execz .LBB0_619
	v_lshl_add_u64 v[18:19], v[32:33], 2, s[8:9]
	s_waitcnt lgkmcnt(0)
	v_add_f32_e32 v16, v16, v17
	global_atomic_add_f32 v[18:19], v16, off
.LBB0_619:
	s_or_b64 exec, exec, s[42:43]
	v_add_u32_e32 v16, 0xb0, v146
	s_waitcnt lgkmcnt(0)
	v_ashrrev_i32_e32 v17, 31, v16
	v_lshlrev_b64 v[18:19], 10, v[16:17]
	v_lshl_add_u64 v[26:27], v[18:19], 0, v[144:145]
	v_lshl_add_u64 v[28:29], v[26:27], 2, s[36:37]
	global_load_dwordx4 v[18:21], v[28:29], off nt
	global_load_dwordx4 v[22:25], v[28:29], off offset:16 nt
	v_fmamk_f32 v30, v154, 0x3b000000, v152
	v_rsq_f32_e32 v30, v30
	v_lshl_add_u64 v[26:27], v[26:27], 1, s[4:5]
	s_waitcnt vmcnt(1)
	v_pk_add_f32 v[20:21], v[14:15], v[20:21]
	v_pk_add_f32 v[18:19], v[12:13], v[18:19]
	s_waitcnt vmcnt(0)
	v_pk_add_f32 v[24:25], v[10:11], v[24:25]
	v_pk_add_f32 v[22:23], v[8:9], v[22:23]
	v_cvt_pk_bf16_f32 v8, v18, v19
	v_cvt_pk_bf16_f32 v9, v20, v21
	v_cvt_pk_bf16_f32 v10, v22, v23
	v_cvt_pk_bf16_f32 v11, v24, v25
	global_store_dwordx4 v[26:27], v[8:11], off
	global_load_dwordx4 v[8:11], v[28:29], off offset:512 nt
	s_nop 0
	global_load_dwordx4 v[12:15], v[28:29], off offset:528 nt
	v_mul_f32_e32 v19, v19, v19
	v_mul_f32_e32 v21, v21, v21
	v_mul_f32_e32 v23, v23, v23
	v_fmac_f32_e32 v19, v18, v18
	v_fmac_f32_e32 v21, v20, v20
	v_mul_f32_e32 v25, v25, v25
	v_fmac_f32_e32 v23, v22, v22
	v_add_f32_e32 v18, v19, v21
	v_fmac_f32_e32 v25, v24, v24
	v_add_f32_e32 v18, v18, v23
	v_add_f32_e32 v18, v25, v18
	s_waitcnt vmcnt(1)
	v_pk_add_f32 v[6:7], v[6:7], v[10:11]
	v_pk_add_f32 v[4:5], v[4:5], v[8:9]
	s_waitcnt vmcnt(0)
	v_pk_add_f32 v[10:11], v[0:1], v[12:13]
	v_mul_f32_e32 v0, v5, v5
	v_mul_f32_e32 v1, v7, v7
	v_pk_add_f32 v[8:9], v[2:3], v[14:15]
	v_mul_f32_e32 v2, v11, v11
	v_fmac_f32_e32 v0, v4, v4
	v_fmac_f32_e32 v1, v6, v6
	v_mul_f32_e32 v3, v9, v9
	v_fmac_f32_e32 v2, v10, v10
	v_add_f32_e32 v0, v0, v1
	v_add_f32_e32 v0, v0, v2
	v_fmac_f32_e32 v3, v8, v8
	v_add_f32_e32 v0, v3, v0
	v_add_f32_e32 v0, v18, v0
	ds_bpermute_b32 v1, v120, v0
	v_cvt_pk_bf16_f32 v2, v4, v5
	v_cvt_pk_bf16_f32 v3, v6, v7
	v_cvt_pk_bf16_f32 v4, v10, v11
	v_cvt_pk_bf16_f32 v5, v8, v9
	s_waitcnt lgkmcnt(0)
	v_add_f32_e32 v0, v0, v1
	ds_bpermute_b32 v1, v114, v0
	global_store_dwordx4 v[26:27], v[2:5], off offset:256
	s_and_saveexec_b64 s[42:43], s[0:1]
	s_cbranch_execz .LBB0_621
	v_lshl_add_u64 v[2:3], v[16:17], 2, s[8:9]
	s_waitcnt lgkmcnt(0)
	v_add_f32_e32 v0, v0, v1
	global_atomic_add_f32 v[2:3], v0, off

.LBB0_765:
	v_lshl_add_u32 v148, s18, 8, v150
	v_lshl_or_b32 v146, s19, 8, v152
	v_ashrrev_i32_e32 v149, 31, v148
	v_ashrrev_i32_e32 v147, 31, v146
	v_lshlrev_b64 v[144:145], 10, v[148:149]
	v_lshl_add_u64 v[144:145], v[144:145], 0, v[146:147]
	v_lshl_add_u64 v[160:161], v[144:145], 1, s[4:5]
	global_load_dwordx4 v[156:159], v[160:161], off nt
	v_lshl_add_u64 v[162:163], v[144:145], 2, s[26:27]
	s_and_b64 vcc, exec, s[0:1]
	s_mov_b64 s[0:1], -1
	s_waitcnt vmcnt(0)
	v_lshlrev_b32_e32 v164, 16, v156
	v_and_b32_e32 v165, 0xffff0000, v156
	v_lshlrev_b32_e32 v156, 16, v157
	v_and_b32_e32 v157, 0xffff0000, v157
	v_lshlrev_b32_e32 v166, 16, v158
	v_and_b32_e32 v167, 0xffff0000, v158
	v_lshlrev_b32_e32 v158, 16, v159
	v_and_b32_e32 v159, 0xffff0000, v159
	v_pk_add_f32 v[126:127], v[126:127], v[156:157]
	v_pk_add_f32 v[124:125], v[124:125], v[164:165]
	v_pk_add_f32 v[122:123], v[122:123], v[158:159]
	v_pk_add_f32 v[120:121], v[120:121], v[166:167]
	global_store_dwordx4 v[162:163], v[124:127], off nt
	global_store_dwordx4 v[162:163], v[120:123], off offset:16 nt
	global_load_dwordx4 v[120:123], v[160:161], off offset:256 nt
	v_or_b32_e32 v124, 16, v148
	v_ashrrev_i32_e32 v125, 31, v124
	v_lshlrev_b64 v[124:125], 10, v[124:125]
	v_lshl_add_u64 v[124:125], v[124:125], 0, v[146:147]
	v_lshl_add_u64 v[126:127], v[124:125], 1, s[4:5]
	s_waitcnt vmcnt(0)
	v_lshlrev_b32_e32 v156, 16, v120
	v_and_b32_e32 v157, 0xffff0000, v120
	v_lshlrev_b32_e32 v120, 16, v121
	v_and_b32_e32 v121, 0xffff0000, v121
	v_lshlrev_b32_e32 v158, 16, v122
	v_and_b32_e32 v159, 0xffff0000, v122
	v_lshlrev_b32_e32 v122, 16, v123
	v_and_b32_e32 v123, 0xffff0000, v123
	v_pk_add_f32 v[114:115], v[114:115], v[120:121]
	v_pk_add_f32 v[112:113], v[112:113], v[156:157]
	v_pk_add_f32 v[110:111], v[110:111], v[122:123]
	v_pk_add_f32 v[108:109], v[108:109], v[158:159]
	global_store_dwordx4 v[162:163], v[112:115], off offset:512 nt
	global_store_dwordx4 v[162:163], v[108:111], off offset:528 nt
	global_load_dwordx4 v[108:111], v[126:127], off nt
	v_lshl_add_u64 v[112:113], v[124:125], 2, s[26:27]
	s_waitcnt vmcnt(0)
	v_lshlrev_b32_e32 v114, 16, v108
	v_and_b32_e32 v115, 0xffff0000, v108
	v_lshlrev_b32_e32 v108, 16, v109
	v_and_b32_e32 v109, 0xffff0000, v109
	v_lshlrev_b32_e32 v120, 16, v110
	v_and_b32_e32 v121, 0xffff0000, v110
	v_lshlrev_b32_e32 v122, 16, v111
	v_and_b32_e32 v123, 0xffff0000, v111
	v_pk_add_f32 v[110:111], v[118:119], v[108:109]
	v_pk_add_f32 v[108:109], v[116:117], v[114:115]
	v_pk_add_f32 v[106:107], v[106:107], v[122:123]
	v_pk_add_f32 v[104:105], v[104:105], v[120:121]
	global_store_dwordx4 v[112:113], v[108:111], off nt
	global_store_dwordx4 v[112:113], v[104:107], off offset:16 nt
	global_load_dwordx4 v[104:107], v[126:127], off offset:256 nt
	v_or_b32_e32 v108, 32, v148
	v_ashrrev_i32_e32 v109, 31, v108
	v_lshlrev_b64 v[108:109], 10, v[108:109]
	v_lshl_add_u64 v[108:109], v[108:109], 0, v[146:147]
	v_lshl_add_u64 v[110:111], v[108:109], 1, s[4:5]
	s_waitcnt vmcnt(0)
	v_lshlrev_b32_e32 v114, 16, v104
	v_and_b32_e32 v115, 0xffff0000, v104
	v_lshlrev_b32_e32 v104, 16, v105
	v_and_b32_e32 v105, 0xffff0000, v105
	v_lshlrev_b32_e32 v116, 16, v106
	v_and_b32_e32 v117, 0xffff0000, v106
	v_lshlrev_b32_e32 v106, 16, v107
	v_and_b32_e32 v107, 0xffff0000, v107
	v_pk_add_f32 v[98:99], v[98:99], v[104:105]
	v_pk_add_f32 v[96:97], v[96:97], v[114:115]
	v_pk_add_f32 v[94:95], v[94:95], v[106:107]
	v_pk_add_f32 v[92:93], v[92:93], v[116:117]
	global_store_dwordx4 v[112:113], v[96:99], off offset:512 nt
	global_store_dwordx4 v[112:113], v[92:95], off offset:528 nt
	global_load_dwordx4 v[92:95], v[110:111], off nt
	v_lshl_add_u64 v[96:97], v[108:109], 2, s[26:27]
	s_waitcnt vmcnt(0)
	v_lshlrev_b32_e32 v98, 16, v92
	v_and_b32_e32 v99, 0xffff0000, v92
	v_lshlrev_b32_e32 v92, 16, v93
	v_and_b32_e32 v93, 0xffff0000, v93
	v_lshlrev_b32_e32 v104, 16, v94
	v_and_b32_e32 v105, 0xffff0000, v94
	v_lshlrev_b32_e32 v106, 16, v95
	v_and_b32_e32 v107, 0xffff0000, v95
	v_pk_add_f32 v[94:95], v[102:103], v[92:93]
	v_pk_add_f32 v[92:93], v[100:101], v[98:99]
	v_pk_add_f32 v[90:91], v[90:91], v[106:107]
	v_pk_add_f32 v[88:89], v[88:89], v[104:105]
	global_store_dwordx4 v[96:97], v[92:95], off nt
	global_store_dwordx4 v[96:97], v[88:91], off offset:16 nt
	global_load_dwordx4 v[88:91], v[110:111], off offset:256 nt
	v_or_b32_e32 v92, 48, v148
	v_ashrrev_i32_e32 v93, 31, v92
	v_lshlrev_b64 v[92:93], 10, v[92:93]
	v_lshl_add_u64 v[92:93], v[92:93], 0, v[146:147]
	v_lshl_add_u64 v[94:95], v[92:93], 1, s[4:5]
	s_waitcnt vmcnt(0)
	v_lshlrev_b32_e32 v98, 16, v88
	v_and_b32_e32 v99, 0xffff0000, v88
	v_lshlrev_b32_e32 v88, 16, v89
	v_and_b32_e32 v89, 0xffff0000, v89
	v_lshlrev_b32_e32 v100, 16, v90
	v_and_b32_e32 v101, 0xffff0000, v90
	v_lshlrev_b32_e32 v90, 16, v91
	v_and_b32_e32 v91, 0xffff0000, v91
	v_pk_add_f32 v[82:83], v[82:83], v[88:89]
	v_pk_add_f32 v[80:81], v[80:81], v[98:99]
	v_pk_add_f32 v[78:79], v[78:79], v[90:91]
	v_pk_add_f32 v[76:77], v[76:77], v[100:101]
	global_store_dwordx4 v[96:97], v[80:83], off offset:512 nt
	global_store_dwordx4 v[96:97], v[76:79], off offset:528 nt
	global_load_dwordx4 v[76:79], v[94:95], off nt
	v_lshl_add_u64 v[80:81], v[92:93], 2, s[26:27]
	s_waitcnt vmcnt(0)
	v_lshlrev_b32_e32 v82, 16, v76
	v_and_b32_e32 v83, 0xffff0000, v76
	v_lshlrev_b32_e32 v76, 16, v77
	v_and_b32_e32 v77, 0xffff0000, v77
	v_lshlrev_b32_e32 v88, 16, v78
	v_and_b32_e32 v89, 0xffff0000, v78
	v_lshlrev_b32_e32 v90, 16, v79
	v_and_b32_e32 v91, 0xffff0000, v79
	v_pk_add_f32 v[78:79], v[86:87], v[76:77]
	v_pk_add_f32 v[76:77], v[84:85], v[82:83]
	v_pk_add_f32 v[74:75], v[74:75], v[90:91]
	v_pk_add_f32 v[72:73], v[72:73], v[88:89]
	global_store_dwordx4 v[80:81], v[76:79], off nt
	global_store_dwordx4 v[80:81], v[72:75], off offset:16 nt
	global_load_dwordx4 v[72:75], v[94:95], off offset:256 nt
	v_lshl_add_u64 v[76:77], v[144:145], 0, s[12:13]
	v_lshl_add_u64 v[78:79], v[76:77], 1, s[4:5]
	s_waitcnt vmcnt(0)
	v_lshlrev_b32_e32 v82, 16, v72
	v_and_b32_e32 v83, 0xffff0000, v72
	v_lshlrev_b32_e32 v72, 16, v73
	v_and_b32_e32 v73, 0xffff0000, v73
	v_lshlrev_b32_e32 v84, 16, v74
	v_and_b32_e32 v85, 0xffff0000, v74
	v_lshlrev_b32_e32 v74, 16, v75
	v_and_b32_e32 v75, 0xffff0000, v75
	v_pk_add_f32 v[70:71], v[70:71], v[72:73]
	v_pk_add_f32 v[68:69], v[68:69], v[82:83]
	v_pk_add_f32 v[66:67], v[66:67], v[74:75]
	v_pk_add_f32 v[64:65], v[64:65], v[84:85]
	global_store_dwordx4 v[80:81], v[68:71], off offset:512 nt
	global_store_dwordx4 v[80:81], v[64:67], off offset:528 nt
	global_load_dwordx4 v[64:67], v[78:79], off nt
	v_lshl_add_u64 v[68:69], v[76:77], 2, s[26:27]
	s_waitcnt vmcnt(0)
	v_lshlrev_b32_e32 v70, 16, v64
	v_and_b32_e32 v71, 0xffff0000, v64
	v_lshlrev_b32_e32 v64, 16, v65
	v_and_b32_e32 v65, 0xffff0000, v65
	v_lshlrev_b32_e32 v72, 16, v66
	v_and_b32_e32 v73, 0xffff0000, v66
	v_lshlrev_b32_e32 v66, 16, v67
	v_and_b32_e32 v67, 0xffff0000, v67
	v_pk_add_f32 v[62:63], v[62:63], v[64:65]
	v_pk_add_f32 v[60:61], v[60:61], v[70:71]
	v_pk_add_f32 v[58:59], v[58:59], v[66:67]
	v_pk_add_f32 v[56:57], v[56:57], v[72:73]
	global_store_dwordx4 v[68:69], v[60:63], off nt
	global_store_dwordx4 v[68:69], v[56:59], off offset:16 nt
	global_load_dwordx4 v[56:59], v[78:79], off offset:256 nt
	v_lshl_add_u64 v[60:61], v[144:145], 0, s[14:15]
	v_lshl_add_u64 v[62:63], v[60:61], 1, s[4:5]
	s_waitcnt vmcnt(0)
	v_lshlrev_b32_e32 v64, 16, v56
	v_and_b32_e32 v65, 0xffff0000, v56
	v_lshlrev_b32_e32 v56, 16, v57
	v_and_b32_e32 v57, 0xffff0000, v57
	v_lshlrev_b32_e32 v66, 16, v58
	v_and_b32_e32 v67, 0xffff0000, v58
	v_lshlrev_b32_e32 v58, 16, v59
	v_and_b32_e32 v59, 0xffff0000, v59
	v_pk_add_f32 v[50:51], v[50:51], v[56:57]
	v_pk_add_f32 v[48:49], v[48:49], v[64:65]
	v_pk_add_f32 v[46:47], v[46:47], v[58:59]
	v_pk_add_f32 v[44:45], v[44:45], v[66:67]
	global_store_dwordx4 v[68:69], v[48:51], off offset:512 nt
	global_store_dwordx4 v[68:69], v[44:47], off offset:528 nt
	global_load_dwordx4 v[44:47], v[62:63], off nt
	v_lshl_add_u64 v[48:49], v[60:61], 2, s[26:27]
	s_waitcnt vmcnt(0)
	v_lshlrev_b32_e32 v50, 16, v44
	v_and_b32_e32 v51, 0xffff0000, v44
	v_lshlrev_b32_e32 v44, 16, v45
	v_and_b32_e32 v45, 0xffff0000, v45
	v_lshlrev_b32_e32 v56, 16, v46
	v_and_b32_e32 v57, 0xffff0000, v46
	v_lshlrev_b32_e32 v58, 16, v47
	v_and_b32_e32 v59, 0xffff0000, v47
	v_pk_add_f32 v[46:47], v[54:55], v[44:45]
	v_pk_add_f32 v[44:45], v[52:53], v[50:51]
	v_pk_add_f32 v[42:43], v[42:43], v[58:59]
	v_pk_add_f32 v[40:41], v[40:41], v[56:57]
	global_store_dwordx4 v[48:49], v[44:47], off nt
	global_store_dwordx4 v[48:49], v[40:43], off offset:16 nt
	global_load_dwordx4 v[40:43], v[62:63], off offset:256 nt
	v_lshl_add_u64 v[44:45], v[144:145], 0, s[20:21]
	v_lshl_add_u64 v[46:47], v[44:45], 1, s[4:5]
	s_waitcnt vmcnt(0)
	v_lshlrev_b32_e32 v50, 16, v40
	v_and_b32_e32 v51, 0xffff0000, v40
	v_lshlrev_b32_e32 v40, 16, v41
	v_and_b32_e32 v41, 0xffff0000, v41
	v_lshlrev_b32_e32 v52, 16, v42
	v_and_b32_e32 v53, 0xffff0000, v42
	v_lshlrev_b32_e32 v42, 16, v43
	v_and_b32_e32 v43, 0xffff0000, v43
	v_pk_add_f32 v[34:35], v[34:35], v[40:41]
	v_pk_add_f32 v[32:33], v[32:33], v[50:51]
	v_pk_add_f32 v[30:31], v[30:31], v[42:43]
	v_pk_add_f32 v[28:29], v[28:29], v[52:53]
	global_store_dwordx4 v[48:49], v[32:35], off offset:512 nt
	global_store_dwordx4 v[48:49], v[28:31], off offset:528 nt
	global_load_dwordx4 v[28:31], v[46:47], off nt
	v_lshl_add_u64 v[32:33], v[44:45], 2, s[26:27]
	s_waitcnt vmcnt(0)
	v_lshlrev_b32_e32 v34, 16, v28
	v_and_b32_e32 v35, 0xffff0000, v28
	v_lshlrev_b32_e32 v28, 16, v29
	v_and_b32_e32 v29, 0xffff0000, v29
	v_lshlrev_b32_e32 v40, 16, v30
	v_and_b32_e32 v41, 0xffff0000, v30
	v_lshlrev_b32_e32 v42, 16, v31
	v_and_b32_e32 v43, 0xffff0000, v31
	v_pk_add_f32 v[30:31], v[38:39], v[28:29]
	v_pk_add_f32 v[28:29], v[36:37], v[34:35]
	v_pk_add_f32 v[26:27], v[26:27], v[42:43]
	v_pk_add_f32 v[24:25], v[24:25], v[40:41]
	global_store_dwordx4 v[32:33], v[28:31], off nt
	global_store_dwordx4 v[32:33], v[24:27], off offset:16 nt
	global_load_dwordx4 v[24:27], v[46:47], off offset:256 nt
	v_lshl_add_u64 v[28:29], v[144:145], 0, s[22:23]
	v_lshl_add_u64 v[30:31], v[28:29], 1, s[4:5]
	s_waitcnt vmcnt(0)
	v_lshlrev_b32_e32 v34, 16, v24
	v_and_b32_e32 v35, 0xffff0000, v24
	v_lshlrev_b32_e32 v24, 16, v25
	v_and_b32_e32 v25, 0xffff0000, v25
	v_lshlrev_b32_e32 v36, 16, v26
	v_and_b32_e32 v37, 0xffff0000, v26
	v_lshlrev_b32_e32 v26, 16, v27
	v_and_b32_e32 v27, 0xffff0000, v27
	v_pk_add_f32 v[18:19], v[18:19], v[24:25]
	v_pk_add_f32 v[16:17], v[16:17], v[34:35]
	v_pk_add_f32 v[14:15], v[14:15], v[26:27]
	v_pk_add_f32 v[12:13], v[12:13], v[36:37]
	global_store_dwordx4 v[32:33], v[16:19], off offset:512 nt
	global_store_dwordx4 v[32:33], v[12:15], off offset:528 nt
	global_load_dwordx4 v[12:15], v[30:31], off nt
	v_lshl_add_u64 v[16:17], v[28:29], 2, s[26:27]
	s_waitcnt vmcnt(0)
	v_lshlrev_b32_e32 v18, 16, v12
	v_and_b32_e32 v19, 0xffff0000, v12
	v_lshlrev_b32_e32 v12, 16, v13
	v_and_b32_e32 v13, 0xffff0000, v13
	v_lshlrev_b32_e32 v24, 16, v14
	v_and_b32_e32 v25, 0xffff0000, v14
	v_lshlrev_b32_e32 v26, 16, v15
	v_and_b32_e32 v27, 0xffff0000, v15
	v_pk_add_f32 v[14:15], v[22:23], v[12:13]
	v_pk_add_f32 v[12:13], v[20:21], v[18:19]
	v_pk_add_f32 v[10:11], v[10:11], v[26:27]
	v_pk_add_f32 v[8:9], v[8:9], v[24:25]
	global_store_dwordx4 v[16:17], v[12:15], off nt
	global_store_dwordx4 v[16:17], v[8:11], off offset:16 nt
	global_load_dwordx4 v[8:11], v[30:31], off offset:256 nt
	s_waitcnt vmcnt(0)
	v_lshlrev_b32_e32 v12, 16, v8
	v_and_b32_e32 v13, 0xffff0000, v8
	v_lshlrev_b32_e32 v8, 16, v9
	v_and_b32_e32 v9, 0xffff0000, v9
	v_lshlrev_b32_e32 v14, 16, v10
	v_and_b32_e32 v15, 0xffff0000, v10
	v_lshlrev_b32_e32 v10, 16, v11
	v_and_b32_e32 v11, 0xffff0000, v11
	v_pk_add_f32 v[6:7], v[6:7], v[8:9]
	v_pk_add_f32 v[4:5], v[4:5], v[12:13]
	v_pk_add_f32 v[2:3], v[2:3], v[10:11]
	v_pk_add_f32 v[0:1], v[0:1], v[14:15]
	global_store_dwordx4 v[16:17], v[4:7], off offset:512 nt
	global_store_dwordx4 v[16:17], v[0:3], off offset:528 nt
	s_cbranch_vccnz .LBB0_750
	s_andn2_b64 vcc, exec, s[6:7]
	s_cbranch_vccnz .LBB0_749
	s_barrier
	s_branch .LBB0_749

	.amdhsa_kernel _Z6mk_fwd4Args
		.amdhsa_group_segment_fixed_size 0
		.amdhsa_private_segment_fixed_size 0
		.amdhsa_kernarg_size 432
		.amdhsa_user_sgpr_count 2
		.amdhsa_user_sgpr_dispatch_ptr 0
		.amdhsa_user_sgpr_queue_ptr 0
		.amdhsa_user_sgpr_kernarg_segment_ptr 1
		.amdhsa_user_sgpr_dispatch_id 0
		.amdhsa_user_sgpr_kernarg_preload_length 0
		.amdhsa_user_sgpr_kernarg_preload_offset 0
		.amdhsa_user_sgpr_private_segment_size 0
		.amdhsa_uses_dynamic_stack 0
		.amdhsa_enable_private_segment 0
		.amdhsa_system_sgpr_workgroup_id_x 1
		.amdhsa_system_sgpr_workgroup_id_y 0
		.amdhsa_system_sgpr_workgroup_id_z 0
		.amdhsa_system_sgpr_workgroup_info 0
		.amdhsa_system_vgpr_workitem_id 2
		.amdhsa_next_free_vgpr 256
		.amdhsa_next_free_sgpr 102
		.amdhsa_accum_offset 256
		.amdhsa_reserve_vcc 1
		.amdhsa_float_round_mode_32 0
		.amdhsa_float_round_mode_16_64 0
		.amdhsa_float_denorm_mode_32 3
		.amdhsa_float_denorm_mode_16_64 3
		.amdhsa_dx10_clamp 1
		.amdhsa_ieee_mode 1
		.amdhsa_fp16_overflow 0
		.amdhsa_tg_split 0
		.amdhsa_exception_fp_ieee_invalid_op 0
		.amdhsa_exception_fp_denorm_src 0
		.amdhsa_exception_fp_ieee_div_zero 0
		.amdhsa_exception_fp_ieee_overflow 0
		.amdhsa_exception_fp_ieee_underflow 0
		.amdhsa_exception_fp_ieee_inexact 0
		.amdhsa_exception_int_div_zero 0
	.end_amdhsa_kernel

amdhsa.kernels:
  - .agpr_count:     0
    .args:
      - .offset:         0
        .size:           176
        .value_kind:     by_value
      - .offset:         176
        .size:           4
        .value_kind:     hidden_block_count_x
      - .offset:         180
        .size:           4
        .value_kind:     hidden_block_count_y
      - .offset:         184
        .size:           4
        .value_kind:     hidden_block_count_z
      - .offset:         188
        .size:           2
        .value_kind:     hidden_group_size_x
      - .offset:         190
        .size:           2
        .value_kind:     hidden_group_size_y
      - .offset:         192
        .size:           2
        .value_kind:     hidden_group_size_z
      - .offset:         194
        .size:           2
        .value_kind:     hidden_remainder_x
      - .offset:         196
        .size:           2
        .value_kind:     hidden_remainder_y
      - .offset:         198
        .size:           2
        .value_kind:     hidden_remainder_z
      - .offset:         216
        .size:           8
        .value_kind:     hidden_global_offset_x
      - .offset:         224
        .size:           8
        .value_kind:     hidden_global_offset_y
      - .offset:         232
        .size:           8
        .value_kind:     hidden_global_offset_z
      - .offset:         240
        .size:           2
        .value_kind:     hidden_grid_dims
      - .offset:         264
        .size:           8
        .value_kind:     hidden_multigrid_sync_arg
      - .offset:         296
        .size:           4
        .value_kind:     hidden_dynamic_lds_size
    .group_segment_fixed_size: 0
    .kernarg_segment_align: 8
    .kernarg_segment_size: 432
    .language:       OpenCL C
    .language_version:
      - 2
      - 0
    .max_flat_workgroup_size: 512
    .name:           _Z6mk_fwd4Args
    .private_segment_fixed_size: 0
    .sgpr_count:     108
    .sgpr_spill_count: 17
    .symbol:         _Z6mk_fwd4Args.kd
    .uniform_work_group_size: 1
    .uses_dynamic_stack: false
    .vgpr_count:     256
    .vgpr_spill_count: 0
    .wavefront_size: 64
